# fold_items rewrite + barrier pollers read TOPGEN + decay-tile epilogue trimmed (exact) + decay tiles scheduled on two-tile workgroups
# speedup vs baseline: 1.0257x; 1.0127x over previous
.LBB0_96:
	s_lshl_b32 s20, s36, 6
	s_add_i32 s2, s20, 0x500
	s_mov_b32 s3, 0
	s_lshl_b64 s[0:1], s[2:3], 2
	s_add_u32 s0, s34, s0
	s_addc_u32 s1, s35, s1
	v_mov_b32_e32 v1, 1
	v_mov_b64_e32 v[4:5], s[0:1]
	flat_atomic_add v1, v[4:5], v1 sc0
	v_cvt_f32_u32_e32 v3, v2
	v_sub_u32_e32 v4, 0, v2
	v_rcp_iflag_f32_e32 v3, v3
	s_nop 0
	v_mul_f32_e32 v3, 0x4f7ffffe, v3
	v_cvt_u32_f32_e32 v3, v3
	v_mul_lo_u32 v4, v4, v3
	v_mul_hi_u32 v4, v3, v4
	v_add_u32_e32 v3, v3, v4
	s_waitcnt vmcnt(0) lgkmcnt(0)
	v_mul_hi_u32 v3, v1, v3
	v_mul_lo_u32 v5, v3, v2
	v_add_u32_e32 v4, 1, v1
	v_sub_u32_e32 v1, v1, v5
	v_add_u32_e32 v6, 1, v3
	v_cmp_ge_u32_e32 vcc, v1, v2
	v_sub_u32_e32 v5, v1, v2
	s_nop 0
	v_cndmask_b32_e32 v3, v3, v6, vcc
	v_cndmask_b32_e32 v1, v1, v5, vcc
	v_add_u32_e32 v5, 1, v3
	v_cmp_ge_u32_e32 vcc, v1, v2
	s_nop 1
	v_cndmask_b32_e32 v1, v3, v5, vcc
	v_mad_u64_u32 v[2:3], s[0:1], v2, v1, v[2:3]
	v_cmp_ne_u32_e32 vcc, v4, v2
	s_and_saveexec_b64 s[0:1], vcc
	s_xor_b64 s[0:1], exec, s[0:1]
	s_cbranch_execz .LBB0_109
	s_movk_i32 s2, 0xd40
	s_lshl_b64 s[2:3], s[2:3], 2
	s_add_u32 s4, s34, s2
	s_addc_u32 s5, s35, s3
	v_mov_b64_e32 v[2:3], s[4:5]
	flat_load_dword v0, v[2:3] sc1
	s_waitcnt vmcnt(0) lgkmcnt(0)
	v_cmp_eq_u32_e32 vcc, v0, v1
	s_and_saveexec_b64 s[2:3], vcc
	s_cbranch_execz .LBB0_108
	s_mov_b32 s21, 1
	s_mov_b64 s[6:7], 0
	s_branch .LBB0_100

.LBB0_125:
	s_or_b64 exec, exec, s[30:31]
	s_lshl_b32 s80, s66, 5
	s_mul_i32 s0, s67, s66
	s_cmpk_lt_i32 s62, 0x294
	s_mul_i32 s73, s0, s37
	s_cselect_b64 s[0:1], -1, 0
	v_writelane_b32 v253, s0, 19
	s_ashr_i32 s90, s62, 31
	s_ashr_i32 s91, s66, 31
	v_writelane_b32 v253, s1, 20
	s_lshr_b32 s0, s90, 29
	s_add_i32 s0, s62, s0
	s_ashr_i32 s2, s0, 3
	s_and_b32 s0, s0, -8
	s_sub_i32 s3, s62, s0
	s_mul_i32 s0, s3, 0x52
	s_add_i32 s0, s0, 4
	s_cmpk_lt_i32 s62, 0x108
	s_cselect_b64 s[4:5], -1, 0
	v_writelane_b32 v253, s4, 21
	s_cmpk_lt_i32 s62, 0x200
	s_mul_i32 s72, s66, 24
	v_writelane_b32 v253, s5, 22
	s_cselect_b64 s[4:5], -1, 0
	v_writelane_b32 v253, s4, 23
	s_cmpk_lt_i32 s62, 0x100
	s_movk_i32 s92, 0x100
	v_writelane_b32 v253, s5, 24
	s_cselect_b64 s[4:5], -1, 0
	v_writelane_b32 v253, s4, 25
	s_cmp_gt_i32 s62, 15
	v_mov_b32_e32 v169, 0
	v_writelane_b32 v253, s5, 26
	s_cselect_b64 s[4:5], -1, 0
	v_writelane_b32 v253, s4, 27
	s_cmp_lt_i32 s62, 32
	v_mov_b32_e32 v206, 0x358637bd
	v_writelane_b32 v253, s5, 28
	s_cselect_b64 s[4:5], -1, 0
	v_writelane_b32 v253, s4, 29
	s_ashr_i32 s8, s62, 3
	s_mov_b32 s6, s8
	v_writelane_b32 v253, s5, 30
	s_and_b32 s4, s62, 1
	s_or_b32 s14, s4, 64
	s_lshl_b32 s5, s14, 19
	v_writelane_b32 v253, s5, 31
	s_ashr_i32 s9, s8, 31
	v_writelane_b32 v253, s6, 32
	s_bfe_u32 s1, s62, 0x20001
	v_mov_b32_e32 v207, 0x260
	v_writelane_b32 v253, s7, 33
	s_lshl_b64 s[6:7], s[8:9], 9
	v_writelane_b32 v253, s6, 34
	v_mov_b32_e32 v208, 0x1000
	v_mov_b32_e32 v209, 1
	v_writelane_b32 v253, s7, 35
	v_writelane_b32 v253, s1, 36
	s_lshl_b32 s1, s1, 19
	v_writelane_b32 v253, s1, 37
	s_lshl_b32 s1, s3, 5
	s_cmpk_lg_i32 s66, 0x100
	s_cselect_b64 s[94:95], -1, 0
	s_cmpk_lt_i32 s62, 0x580
	s_cselect_b64 s[6:7], -1, 0
	v_writelane_b32 v253, s6, 38
	s_add_i32 s5, s62, 0xffffff80
	v_mov_b32_e32 v210, 0x41b17218
	v_writelane_b32 v253, s7, 39
	s_lshr_b32 s6, s5, 1
	s_cmpk_lt_i32 s62, 0x58
	s_cselect_b64 s[8:9], -1, 0
	s_cmp_lt_i32 s3, 4
	s_mul_i32 s7, s3, 0x53
	s_cselect_b32 s0, s7, s0
	s_add_i32 s0, s0, s2
	v_writelane_b32 v253, s8, 40
	s_mul_hi_i32 s7, s0, 0x66666667
	v_mov_b32_e32 v252, 0x83
	v_writelane_b32 v253, s9, 41
	s_lshr_b32 s8, s7, 31
	s_ashr_i32 s7, s7, 4
	s_add_i32 s7, s7, s8
	s_lshl_b32 s8, s7, 2
	s_sub_i32 s9, 0x42, s8
	s_mul_i32 s7, s7, 40
	s_min_u32 s9, s9, 4
	s_sub_i32 s7, s0, s7
	s_cmp_lt_i32 s3, 0
	s_mul_i32 s0, s3, 33
	s_cselect_b32 s0, s0, s1
	s_movk_i32 s1, 0xb1
	s_cselect_b32 s10, s1, 0xb0
	s_add_i32 s0, s0, s2
	s_ashr_i32 s1, s0, 31
	s_lshr_b32 s1, s1, 28
	s_add_i32 s1, s0, s1
	s_ashr_i32 s11, s1, 4
	s_and_b32 s1, s1, 0xfff0
	s_sub_i32 s1, s0, s1
	s_bfe_i32 s0, s1, 0x80000
	s_bfe_u32 s0, s0, 0x2000d
	s_add_i32 s12, s1, s0
	s_bfe_i32 s0, s12, 0x80000
	s_and_b32 s12, s12, 0xfc
	s_sub_i32 s1, s1, s12
	s_lshl_b32 s11, s11, 2
	s_sext_i32_i8 s1, s1
	s_sext_i32_i16 s13, s0
	s_add_i32 s12, s11, s1
	s_lshr_b32 s0, s13, 2
	s_ashr_i32 s11, s13, 2
	s_ashr_i32 s13, s12, 31
	s_lshl_b64 s[16:17], s[12:13], 19
	v_writelane_b32 v253, s16, 42
	s_bfe_i64 s[0:1], s[0:1], 0x100000
	s_lshl_b64 s[0:1], s[0:1], 19
	v_writelane_b32 v253, s17, 43
	v_writelane_b32 v253, s0, 44
	v_cvt_f32_ubyte0_e32 v1, s9
	v_cvt_f32_i32_e32 v0, s7
	v_writelane_b32 v253, s1, 45
	s_mul_i32 s0, s3, s10
	s_add_i32 s0, s0, s2
	s_mul_hi_i32 s1, s0, 0x2e8ba2e9
	s_lshr_b32 s2, s1, 31
	s_ashr_i32 s1, s1, 4
	s_add_i32 s1, s1, s2
	s_lshl_b32 s2, s1, 2
	s_mulk_i32 s1, 0x58
	s_sub_i32 s1, s0, s1
	s_bfe_i32 s0, s1, 0x80000
	s_bfe_u32 s0, s0, 0x2000d
	s_add_i32 s3, s1, s0
	s_bfe_i32 s0, s3, 0x80000
	s_and_b32 s3, s3, 0xfc
	s_sub_i32 s1, s1, s3
	s_sext_i32_i16 s10, s0
	s_sext_i32_i8 s1, s1
	s_add_i32 s16, s2, s1
	s_ashr_i32 s1, s10, 2
	v_writelane_b32 v253, s1, 46
	s_mov_b32 s2, s16
	s_ashr_i32 s17, s16, 31
	v_writelane_b32 v253, s2, 47
	s_lshr_b32 s0, s10, 2
	s_bfe_i64 s[0:1], s[0:1], 0x100000
	v_writelane_b32 v253, s3, 48
	s_lshl_b64 s[2:3], s[16:17], 19
	v_writelane_b32 v253, s2, 49
	s_lshl_b64 s[0:1], s[0:1], 19
	s_cmp_lt_u32 s5, 44
	v_writelane_b32 v253, s3, 50
	v_writelane_b32 v253, s0, 51
	v_rcp_iflag_f32_e32 v2, v1
	s_mov_b32 s57, 0xf800000
	v_writelane_b32 v253, s1, 52
	s_cselect_b64 s[0:1], -1, 0
	v_writelane_b32 v253, s0, 53
	v_mul_f32_e32 v2, v0, v2
	v_trunc_f32_e32 v2, v2
	v_writelane_b32 v253, s1, 54
	s_lshl_b32 s0, s6, 7
	v_writelane_b32 v253, s0, 55
	s_lshl_b32 s0, s14, 8
	v_writelane_b32 v253, s14, 56
	s_or_b32 s1, s0, 0x80
	v_writelane_b32 v253, s1, 57
	s_or_b32 s1, s0, 0x90
	v_writelane_b32 v253, s1, 58
	s_or_b32 s1, s0, 0xa0
	v_writelane_b32 v253, s1, 59
	v_writelane_b32 v253, s0, 60
	s_or_b32 s0, s0, 0xb0
	v_writelane_b32 v253, s0, 61
	s_mul_hi_i32 s0, s12, 0x160000
	v_writelane_b32 v253, s0, 62
	s_mov_b32 s0, s12
	v_writelane_b32 v253, s0, 63
	v_fma_f32 v0, -v2, v1, v0
	v_cvt_i32_f32_e32 v2, v2
	v_writelane_b32 v254, s1, 0
	s_mul_i32 s0, s12, 0x160000
	v_writelane_b32 v254, s0, 1
	s_mul_hi_i32 s0, s11, 0x160000
	v_writelane_b32 v254, s0, 2
	v_writelane_b32 v254, s11, 3
	s_mul_i32 s0, s11, 0x160000
	v_writelane_b32 v254, s0, 4
	s_ashr_i32 s0, s7, 30
	s_lshl_b32 s3, s6, 19
	s_or_b32 s2, s0, 1
	v_cmp_ge_f32_e64 s[0:1], |v0|, v1
	s_and_b64 s[0:1], s[0:1], exec
	s_cselect_b32 s0, s2, 0
	v_readfirstlane_b32 s1, v2
	s_add_i32 s0, s1, s0
	s_sext_i32_i8 s1, s0
	s_mul_i32 s0, s0, s9
	s_sub_i32 s0, s7, s0
	s_sext_i32_i8 s0, s0
	v_writelane_b32 v254, s1, 5
	s_add_i32 s0, s8, s0
	s_ashr_i32 s81, s80, 31
	v_writelane_b32 v254, s0, 6
	s_cmp_lt_u32 s62, 0x194
	s_cselect_b32 s7, 0, 66
	s_sub_i32 s7, s62, s7
	s_and_b32 s8, s7, 7
	s_lshr_b32 s7, s7, 3
	s_mul_i32 s9, s8, 0x4a
	s_min_u32 s8, s8, 2
	s_add_i32 s7, s7, s9
	s_add_i32 s7, s7, s8
	s_mul_i32 s8, s7, 0x71d
	s_lshr_b32 s8, s8, 16
	s_mul_i32 s9, s8, 36
	s_sub_i32 s9, s7, s9
	s_cmp_gt_u32 s9, 7
	s_cselect_b32 s5, 4, 0
	s_add_i32 s9, s9, s5
	s_and_b32 s6, s9, 3
	s_lshl_b32 s8, s8, 2
	s_add_i32 s6, s6, s8
	s_lshr_b32 s5, s9, 2
	s_cmp_gt_u32 s7, 0x23f
	s_cbranch_scc0 .Ltm_p2f_a
	s_sub_i32 s9, s7, 0x240
	s_cmp_gt_u32 s9, 3
	s_cselect_b32 s8, 2, 0
	s_add_i32 s9, s9, s8
	s_and_b32 s6, s9, 1
	s_or_b32 s6, s6, 64
	s_lshr_b32 s5, s9, 1
.Ltm_p2f_a:
	s_sub_i32 s7, s62, 0x194
	s_cmp_lt_u32 s7, 66
	s_cselect_b32 s6, s7, s6
	s_cselect_b32 s5, 2, s5
	v_writelane_b32 v254, s5, 5
	v_writelane_b32 v254, s6, 6
	s_lshl_b64 s[0:1], s[80:81], 12
	v_writelane_b32 v254, s0, 7
	s_ashr_i32 s71, s70, 31
	s_lshl_b32 s67, s66, 4
	v_writelane_b32 v254, s1, 8
	s_lshl_b32 s0, s62, 6
	s_addk_i32 s0, 0x4000
	v_writelane_b32 v254, s0, 9
	s_lshl_b32 s0, s62, 7
	v_writelane_b32 v254, s0, 10
	s_lshl_b32 s0, s62, 5
	v_writelane_b32 v254, s0, 11
	s_lshl_b32 s0, s62, 8
	v_writelane_b32 v254, s0, 12
	s_lshl_b32 s0, s62, 4
	v_writelane_b32 v254, s0, 13
	s_lshl_b64 s[0:1], s[70:71], 12
	v_writelane_b32 v254, s0, 14
	s_lshl_b64 s[96:97], s[80:81], 11
	s_lshl_b64 s[58:59], s[70:71], 11
	s_lshl_b32 s81, s66, 7
	s_lshl_b32 s93, s66, 8
	v_writelane_b32 v254, s1, 15
	v_writelane_b32 v254, s3, 16
	s_add_u32 s0, s3, 0x900100
	v_writelane_b32 v254, s0, 17
	s_addc_u32 s0, 0, 0
	v_writelane_b32 v254, s0, 18
	s_lshl_b32 s0, s4, 19
	s_mov_b32 s3, 0x20000
	s_mov_b32 s2, 0x5ac0000
	v_writelane_b32 v253, s0, 0
	s_movk_i32 s71, 0x4000
	s_movk_i32 s77, 0x7fff
	v_writelane_b32 v253, s1, 1
	v_writelane_b32 v253, s2, 2
	v_writelane_b32 v253, s3, 3
	v_writelane_b32 v254, s0, 19
	s_or_b32 s0, s0, 0x5240080
	v_writelane_b32 v254, s0, 20
	s_add_i32 s0, 0, 0x20020
	v_writelane_b32 v254, s0, 21
	s_add_i32 s0, 0, 0x20024
	v_writelane_b32 v254, s0, 22
	s_add_i32 s0, 0, 0x20400
	v_writelane_b32 v254, s0, 23
	s_mov_b32 s1, 1
	v_writelane_b32 v254, s0, 24
	s_movk_i32 s33, 0x1000
	s_mov_b32 s84, 0xbfb8aa3b
	v_writelane_b32 v254, s1, 25
	v_writelane_b32 v254, s70, 26
	s_mov_b32 s85, 0x800000
	s_mov_b32 s86, 0x3f317217
	v_writelane_b32 v254, s71, 27
	v_writelane_b32 v254, s69, 28
	v_writelane_b32 v254, s67, 29
	v_writelane_b32 v254, s72, 30
	v_writelane_b32 v254, s80, 31
	s_mov_b32 s87, 0x7f800000
	s_movk_i32 s88, 0x1400
	v_writelane_b32 v254, s81, 32
	v_writelane_b32 v254, s73, 33
	v_writelane_b32 v254, s90, 34
	v_writelane_b32 v254, s91, 35
	v_writelane_b32 v254, s94, 36
	s_mov_b32 s89, 0x5040100
	s_mov_b32 s5, 0
	v_writelane_b32 v254, s95, 37
	v_writelane_b32 v254, s96, 38
	s_mov_b32 s83, 0
	s_mov_b64 s[2:3], 0
	v_writelane_b32 v254, s97, 39
	v_writelane_b32 v254, s58, 40
	s_mov_b64 s[52:53], -1
	s_mov_b64 s[74:75], 0x80
	v_writelane_b32 v254, s59, 41
	v_writelane_b32 v254, s81, 42
	s_mov_b32 s76, 0x3d800000
	v_writelane_b32 v254, s93, 43
	s_waitcnt lgkmcnt(0)
	s_barrier
	s_branch .LBB0_129

.LBB0_188:
	s_lshl_b32 s20, s36, 6
	s_add_i32 s82, s20, 0x500
	s_lshl_b64 s[0:1], s[82:83], 2
	s_add_u32 s0, s34, s0
	s_addc_u32 s1, s35, s1
	v_mov_b64_e32 v[4:5], s[0:1]
	flat_atomic_add v1, v[4:5], v209 sc0
	v_cvt_f32_u32_e32 v3, v2
	v_sub_u32_e32 v4, 0, v2
	v_rcp_iflag_f32_e32 v3, v3
	s_nop 0
	v_mul_f32_e32 v3, 0x4f7ffffe, v3
	v_cvt_u32_f32_e32 v3, v3
	v_mul_lo_u32 v4, v4, v3
	v_mul_hi_u32 v4, v3, v4
	v_add_u32_e32 v3, v3, v4
	s_waitcnt vmcnt(0) lgkmcnt(0)
	v_mul_hi_u32 v3, v1, v3
	v_mul_lo_u32 v5, v3, v2
	v_add_u32_e32 v4, 1, v1
	v_sub_u32_e32 v1, v1, v5
	v_add_u32_e32 v6, 1, v3
	v_cmp_ge_u32_e32 vcc, v1, v2
	v_sub_u32_e32 v5, v1, v2
	s_nop 0
	v_cndmask_b32_e32 v3, v3, v6, vcc
	v_cndmask_b32_e32 v1, v1, v5, vcc
	v_add_u32_e32 v5, 1, v3
	v_cmp_ge_u32_e32 vcc, v1, v2
	s_nop 1
	v_cndmask_b32_e32 v1, v3, v5, vcc
	v_mad_u64_u32 v[2:3], s[0:1], v2, v1, v[2:3]
	v_cmp_ne_u32_e32 vcc, v4, v2
	s_and_saveexec_b64 s[0:1], vcc
	s_xor_b64 s[0:1], exec, s[0:1]
	s_cbranch_execz .LBB0_201
	s_movk_i32 s82, 0xd40
	s_lshl_b64 s[2:3], s[82:83], 2
	s_add_u32 s4, s34, s2
	s_addc_u32 s5, s35, s3
	v_mov_b64_e32 v[2:3], s[4:5]
	flat_load_dword v0, v[2:3] sc1
	s_waitcnt vmcnt(0) lgkmcnt(0)
	v_cmp_eq_u32_e32 vcc, v0, v1
	s_and_saveexec_b64 s[2:3], vcc
	s_cbranch_execz .LBB0_200
	s_mov_b32 s21, 1
	s_mov_b64 s[6:7], 0
	s_branch .LBB0_192

.LBB0_230:
	s_ashr_i32 s7, s7, 3
	s_add_i32 s7, s17, s7
	s_mul_hi_i32 s14, s7, 0x66666667
	s_lshr_b32 s15, s14, 31
	s_ashr_i32 s14, s14, 4
	s_add_i32 s14, s14, s15
	s_lshl_b32 s15, s14, 2
	s_sub_i32 s16, 0x42, s15
	s_min_i32 s16, s16, 4
	s_abs_i32 s17, s16
	v_cvt_f32_u32_e32 v0, s17
	s_sub_i32 s19, 0, s17
	s_mul_i32 s14, s14, 40
	s_sub_i32 s7, s7, s14
	v_rcp_iflag_f32_e32 v0, v0
	s_abs_i32 s14, s7
	s_xor_b32 s18, s7, s16
	s_ashr_i32 s18, s18, 31
	v_mul_f32_e32 v0, 0x4f7ffffe, v0
	v_cvt_u32_f32_e32 v0, v0
	s_nop 0
	v_readfirstlane_b32 s20, v0
	s_mul_i32 s19, s19, s20
	s_mul_hi_u32 s19, s20, s19
	s_add_i32 s20, s20, s19
	s_mul_hi_u32 s19, s14, s20
	s_mul_i32 s20, s19, s17
	s_sub_i32 s14, s14, s20
	s_add_i32 s21, s19, 1
	s_sub_i32 s20, s14, s17
	s_cmp_ge_u32 s14, s17
	s_cselect_b32 s19, s21, s19
	s_cselect_b32 s14, s20, s14
	s_add_i32 s20, s19, 1
	s_cmp_ge_u32 s14, s17
	s_cselect_b32 s14, s20, s19
	s_xor_b32 s14, s14, s18
	s_sub_i32 s14, s14, s18
	s_mul_i32 s16, s14, s16
	s_sub_i32 s7, s7, s16
	s_add_i32 s16, s15, s7
	s_lshl_b32 s20, s40, 8
	s_add_i32 s20, s20, s62
	s_cmp_lt_u32 s20, 0x194
	s_cselect_b32 s17, 0, 66
	s_sub_i32 s17, s20, s17
	s_and_b32 s18, s17, 7
	s_lshr_b32 s17, s17, 3
	s_mul_i32 s19, s18, 0x4a
	s_min_u32 s18, s18, 2
	s_add_i32 s17, s17, s19
	s_add_i32 s17, s17, s18
	s_mul_i32 s18, s17, 0x71d
	s_lshr_b32 s18, s18, 16
	s_mul_i32 s19, s18, 36
	s_sub_i32 s19, s17, s19
	s_cmp_gt_u32 s19, 7
	s_cselect_b32 s14, 4, 0
	s_add_i32 s19, s19, s14
	s_and_b32 s16, s19, 3
	s_lshl_b32 s18, s18, 2
	s_add_i32 s16, s16, s18
	s_lshr_b32 s14, s19, 2
	s_cmp_gt_u32 s17, 0x23f
	s_cbranch_scc0 .Ltm_p2n_a
	s_sub_i32 s19, s17, 0x240
	s_cmp_gt_u32 s19, 3
	s_cselect_b32 s18, 2, 0
	s_add_i32 s19, s19, s18
	s_and_b32 s16, s19, 1
	s_or_b32 s16, s16, 64
	s_lshr_b32 s14, s19, 1
.Ltm_p2n_a:
	s_sub_i32 s17, s20, 0x194
	s_cmp_lt_u32 s17, 66
	s_cselect_b32 s16, s17, s16
	s_cselect_b32 s14, 2, s14

.LBB0_235:
	v_lshl_or_b32 v148, s22, 8, v152
	s_cmp_eq_u32 s22, 2
	v_ashrrev_i32_e32 v149, 31, v148
	s_cselect_b64 s[24:25], -1, 0
	s_cmp_lg_u32 s22, 2
	v_lshl_add_u64 v[146:147], v[148:149], 2, s[10:11]
	s_cbranch_scc1 .LBB0_237
	global_load_dwordx4 v[128:131], v[146:147], off offset:-2032
	global_load_dwordx4 v[132:135], v[146:147], off offset:-2048
	s_waitcnt vmcnt(0)
	v_add_f32_e32 v128, v124, v128
	v_add_f32_e32 v132, v120, v132
	v_mul_f32_e64 v124, |v132|, s84
	v_exp_f32_e32 v124, v124
	v_min_f32_e32 v120, 0, v132
	v_add_f32_e32 v133, v121, v133
	v_add_f32_e32 v129, v125, v129
	v_add_f32_e32 v124, 1.0, v124
	v_mul_f32_e64 v125, |v133|, s84
	v_exp_f32_e32 v125, v125
	v_log_f32_e32 v124, v124
	v_add_f32_e32 v125, 1.0, v125
	v_min_f32_e32 v121, 0, v133
	v_add_f32_e32 v134, v122, v134
	v_mul_f32_e32 v132, 0x3f317217, v124
	v_fma_f32 v132, v124, s86, -v132
	v_fmac_f32_e32 v132, 0x3377d1cf, v124
	v_fmac_f32_e32 v132, 0x3f317217, v124
	v_min_f32_e32 v122, 0, v134
	v_add_f32_e32 v135, v123, v135
	v_mov_b32_e32 v124, v132
	v_min_f32_e32 v124, 0, v128
	v_mul_f32_e64 v128, |v128|, s84
	v_exp_f32_e32 v128, v128
	v_min_f32_e32 v123, 0, v135
	v_add_f32_e32 v128, 1.0, v128
	v_log_f32_e32 v128, v128
	s_nop 0
	v_mul_f32_e32 v154, 0x3f317217, v128
	v_fma_f32 v154, v128, s86, -v154
	v_fmac_f32_e32 v154, 0x3377d1cf, v128
	v_fmac_f32_e32 v154, 0x3f317217, v128
	v_mov_b32_e32 v128, v154
	v_log_f32_e32 v125, v125
	s_nop 0
	v_mul_f32_e32 v133, 0x3f317217, v125
	v_fma_f32 v133, v125, s86, -v133
	v_fmac_f32_e32 v133, 0x3377d1cf, v125
	v_fmac_f32_e32 v133, 0x3f317217, v125
	v_mov_b32_e32 v125, v133
	v_min_f32_e32 v125, 0, v129
	v_mul_f32_e64 v129, |v129|, s84
	v_exp_f32_e32 v129, v129
	v_pk_add_f32 v[120:121], v[120:121], v[132:133] neg_lo:[0,1] neg_hi:[0,1]
	v_add_f32_e32 v129, 1.0, v129
	v_pk_mul_f32 v[120:121], v[120:121], s[76:77] op_sel_hi:[1,0]
	v_log_f32_e32 v129, v129
	s_nop 0
	v_mul_f32_e32 v154, 0x3f317217, v129
	v_fma_f32 v154, v129, s86, -v154
	v_fmac_f32_e32 v154, 0x3377d1cf, v129
	v_fmac_f32_e32 v154, 0x3f317217, v129
	v_mov_b32_e32 v129, v154
	v_add_f32_e32 v154, v126, v130
	v_mul_f32_e64 v126, |v134|, s84
	v_exp_f32_e32 v126, v126
	v_mul_f32_e64 v134, |v154|, s84
	v_exp_f32_e32 v134, v134
	v_pk_add_f32 v[124:125], v[124:125], v[128:129] neg_lo:[0,1] neg_hi:[0,1]
	v_add_f32_e32 v126, 1.0, v126
	v_add_f32_e32 v134, 1.0, v134
	v_pk_mul_f32 v[124:125], v[124:125], s[76:77] op_sel_hi:[1,0]
	v_log_f32_e32 v126, v126
	s_nop 0
	v_mul_f32_e32 v130, 0x3f317217, v126
	v_fma_f32 v130, v126, s86, -v130
	v_fmac_f32_e32 v130, 0x3377d1cf, v126
	v_fmac_f32_e32 v130, 0x3f317217, v126
	v_mov_b32_e32 v126, v130
	v_min_f32_e32 v126, 0, v154
	v_log_f32_e32 v134, v134
	s_nop 0
	v_mul_f32_e32 v154, 0x3f317217, v134
	v_fma_f32 v154, v134, s86, -v154
	v_fmac_f32_e32 v154, 0x3377d1cf, v134
	v_fmac_f32_e32 v154, 0x3f317217, v134
	v_mov_b32_e32 v134, v154
	v_add_f32_e32 v154, v127, v131
	v_mul_f32_e64 v127, |v135|, s84
	v_exp_f32_e32 v127, v127
	s_nop 0
	v_add_f32_e32 v127, 1.0, v127
	v_log_f32_e32 v127, v127
	s_nop 0
	v_mul_f32_e32 v131, 0x3f317217, v127
	v_fma_f32 v131, v127, s86, -v131
	v_fmac_f32_e32 v131, 0x3377d1cf, v127
	v_fmac_f32_e32 v131, 0x3f317217, v127
	v_mov_b32_e32 v127, v131
	v_pk_add_f32 v[122:123], v[122:123], v[130:131] neg_lo:[0,1] neg_hi:[0,1]
	v_mul_f32_e64 v130, |v154|, s84
	v_exp_f32_e32 v130, v130
	v_min_f32_e32 v127, 0, v154
	v_pk_mul_f32 v[122:123], v[122:123], s[76:77] op_sel_hi:[1,0]
	v_add_f32_e32 v130, 1.0, v130
	v_log_f32_e32 v130, v130
	s_nop 0
	v_mul_f32_e32 v131, 0x3f317217, v130
	v_fma_f32 v131, v130, s86, -v131
	v_fmac_f32_e32 v131, 0x3377d1cf, v130
	v_fmac_f32_e32 v131, 0x3f317217, v130
	v_mov_b32_e32 v130, v131
	v_mov_b32_e32 v135, v130
	v_pk_add_f32 v[126:127], v[126:127], v[134:135] neg_lo:[0,1] neg_hi:[0,1]
	v_pk_mul_f32 v[126:127], v[126:127], s[76:77] op_sel_hi:[1,0]
.LBB0_237:
	v_lshl_add_u32 v130, s6, 8, v150
	v_mov_b64_e32 v[128:129], s[8:9]
	v_mad_i64_i32 v[128:129], s[0:1], v130, s88, v[128:129]
	v_cvt_pk_bf16_f32 v120, v120, v121
	v_cvt_pk_bf16_f32 v121, v122, v123
	v_cvt_pk_bf16_f32 v122, v124, v125
	v_cndmask_b32_e64 v124, 0, 1, s[24:25]
	v_lshl_add_u64 v[128:129], v[148:149], 1, v[128:129]
	v_cmp_ne_u32_e64 s[6:7], 1, v124
	s_andn2_b64 vcc, exec, s[24:25]
	v_cvt_pk_bf16_f32 v123, v126, v127
	flat_store_dwordx4 v[128:129], v[120:123]
	s_cbranch_vccnz .LBB0_239
	global_load_dwordx4 v[120:123], v[146:147], off offset:-1520
	global_load_dwordx4 v[124:127], v[146:147], off offset:-1536
	s_waitcnt vmcnt(0)
	v_add_f32_e32 v120, v116, v120
	v_add_f32_e32 v124, v112, v124
	v_mul_f32_e64 v116, |v124|, s84
	v_exp_f32_e32 v116, v116
	v_min_f32_e32 v112, 0, v124
	v_add_f32_e32 v125, v113, v125
	v_add_f32_e32 v121, v117, v121
	v_add_f32_e32 v116, 1.0, v116
	v_mul_f32_e64 v117, |v125|, s84
	v_exp_f32_e32 v117, v117
	v_log_f32_e32 v116, v116
	v_add_f32_e32 v117, 1.0, v117
	v_min_f32_e32 v113, 0, v125
	v_add_f32_e32 v126, v114, v126
	v_mul_f32_e32 v124, 0x3f317217, v116
	v_fma_f32 v124, v116, s86, -v124
	v_fmac_f32_e32 v124, 0x3377d1cf, v116
	v_fmac_f32_e32 v124, 0x3f317217, v116
	v_min_f32_e32 v114, 0, v126
	v_add_f32_e32 v127, v115, v127
	v_mov_b32_e32 v116, v124
	v_min_f32_e32 v116, 0, v120
	v_mul_f32_e64 v120, |v120|, s84
	v_exp_f32_e32 v120, v120
	v_min_f32_e32 v115, 0, v127
	v_add_f32_e32 v120, 1.0, v120
	v_log_f32_e32 v120, v120
	s_nop 0
	v_mul_f32_e32 v131, 0x3f317217, v120
	v_fma_f32 v131, v120, s86, -v131
	v_fmac_f32_e32 v131, 0x3377d1cf, v120
	v_fmac_f32_e32 v131, 0x3f317217, v120
	v_mov_b32_e32 v120, v131
	v_log_f32_e32 v117, v117
	s_nop 0
	v_mul_f32_e32 v125, 0x3f317217, v117
	v_fma_f32 v125, v117, s86, -v125
	v_fmac_f32_e32 v125, 0x3377d1cf, v117
	v_fmac_f32_e32 v125, 0x3f317217, v117
	v_mov_b32_e32 v117, v125
	v_min_f32_e32 v117, 0, v121
	v_mul_f32_e64 v121, |v121|, s84
	v_exp_f32_e32 v121, v121
	v_pk_add_f32 v[112:113], v[112:113], v[124:125] neg_lo:[0,1] neg_hi:[0,1]
	v_add_f32_e32 v121, 1.0, v121
	v_pk_mul_f32 v[112:113], v[112:113], s[76:77] op_sel_hi:[1,0]
	v_log_f32_e32 v121, v121
	s_nop 0
	v_mul_f32_e32 v131, 0x3f317217, v121
	v_fma_f32 v131, v121, s86, -v131
	v_fmac_f32_e32 v131, 0x3377d1cf, v121
	v_fmac_f32_e32 v131, 0x3f317217, v121
	v_mov_b32_e32 v121, v131
	v_add_f32_e32 v131, v118, v122
	v_mul_f32_e64 v118, |v126|, s84
	v_exp_f32_e32 v118, v118
	v_mul_f32_e64 v126, |v131|, s84
	v_exp_f32_e32 v126, v126
	v_pk_add_f32 v[116:117], v[116:117], v[120:121] neg_lo:[0,1] neg_hi:[0,1]
	v_add_f32_e32 v118, 1.0, v118
	v_add_f32_e32 v126, 1.0, v126
	v_pk_mul_f32 v[116:117], v[116:117], s[76:77] op_sel_hi:[1,0]
	v_log_f32_e32 v118, v118
	s_nop 0
	v_mul_f32_e32 v122, 0x3f317217, v118
	v_fma_f32 v122, v118, s86, -v122
	v_fmac_f32_e32 v122, 0x3377d1cf, v118
	v_fmac_f32_e32 v122, 0x3f317217, v118
	v_mov_b32_e32 v118, v122
	v_min_f32_e32 v118, 0, v131
	v_log_f32_e32 v126, v126
	s_nop 0
	v_mul_f32_e32 v131, 0x3f317217, v126
	v_fma_f32 v131, v126, s86, -v131
	v_fmac_f32_e32 v131, 0x3377d1cf, v126
	v_fmac_f32_e32 v131, 0x3f317217, v126
	v_mov_b32_e32 v126, v131
	v_add_f32_e32 v131, v119, v123
	v_mul_f32_e64 v119, |v127|, s84
	v_exp_f32_e32 v119, v119
	s_nop 0
	v_add_f32_e32 v119, 1.0, v119
	v_log_f32_e32 v119, v119
	s_nop 0
	v_mul_f32_e32 v123, 0x3f317217, v119
	v_fma_f32 v123, v119, s86, -v123
	v_fmac_f32_e32 v123, 0x3377d1cf, v119
	v_fmac_f32_e32 v123, 0x3f317217, v119
	v_mov_b32_e32 v119, v123
	v_pk_add_f32 v[114:115], v[114:115], v[122:123] neg_lo:[0,1] neg_hi:[0,1]
	v_mul_f32_e64 v122, |v131|, s84
	v_exp_f32_e32 v122, v122
	v_min_f32_e32 v119, 0, v131
	v_pk_mul_f32 v[114:115], v[114:115], s[76:77] op_sel_hi:[1,0]
	v_add_f32_e32 v122, 1.0, v122
	v_log_f32_e32 v122, v122
	s_nop 0
	v_mul_f32_e32 v123, 0x3f317217, v122
	v_fma_f32 v123, v122, s86, -v123
	v_fmac_f32_e32 v123, 0x3377d1cf, v122
	v_fmac_f32_e32 v123, 0x3f317217, v122
	v_mov_b32_e32 v122, v123
	v_mov_b32_e32 v127, v122
	v_pk_add_f32 v[118:119], v[118:119], v[126:127] neg_lo:[0,1] neg_hi:[0,1]
	v_pk_mul_f32 v[118:119], v[118:119], s[76:77] op_sel_hi:[1,0]
.LBB0_239:
	s_and_b64 vcc, exec, s[6:7]
	v_cvt_pk_bf16_f32 v112, v112, v113
	v_cvt_pk_bf16_f32 v113, v114, v115
	v_cvt_pk_bf16_f32 v114, v116, v117
	v_cvt_pk_bf16_f32 v115, v118, v119
	flat_store_dwordx4 v[128:129], v[112:115] offset:256
	s_cbranch_vccnz .LBB0_241
	global_load_dwordx4 v[112:115], v[146:147], off offset:-2032
	global_load_dwordx4 v[116:119], v[146:147], off offset:-2048
	s_waitcnt vmcnt(0)
	v_add_f32_e32 v112, v108, v112
	v_add_f32_e32 v116, v104, v116
	v_mul_f32_e64 v108, |v116|, s84
	v_exp_f32_e32 v108, v108
	v_min_f32_e32 v104, 0, v116
	v_add_f32_e32 v117, v105, v117
	v_add_f32_e32 v113, v109, v113
	v_add_f32_e32 v108, 1.0, v108
	v_mul_f32_e64 v109, |v117|, s84
	v_exp_f32_e32 v109, v109
	v_log_f32_e32 v108, v108
	v_add_f32_e32 v109, 1.0, v109
	v_min_f32_e32 v105, 0, v117
	v_add_f32_e32 v118, v106, v118
	v_mul_f32_e32 v116, 0x3f317217, v108
	v_fma_f32 v116, v108, s86, -v116
	v_fmac_f32_e32 v116, 0x3377d1cf, v108
	v_fmac_f32_e32 v116, 0x3f317217, v108
	v_min_f32_e32 v106, 0, v118
	v_add_f32_e32 v119, v107, v119
	v_mov_b32_e32 v108, v116
	v_min_f32_e32 v108, 0, v112
	v_mul_f32_e64 v112, |v112|, s84
	v_exp_f32_e32 v112, v112
	v_min_f32_e32 v107, 0, v119
	v_add_f32_e32 v112, 1.0, v112
	v_log_f32_e32 v112, v112
	s_nop 0
	v_mul_f32_e32 v120, 0x3f317217, v112
	v_fma_f32 v120, v112, s86, -v120
	v_fmac_f32_e32 v120, 0x3377d1cf, v112
	v_fmac_f32_e32 v120, 0x3f317217, v112
	v_mov_b32_e32 v112, v120
	v_log_f32_e32 v109, v109
	s_nop 0
	v_mul_f32_e32 v117, 0x3f317217, v109
	v_fma_f32 v117, v109, s86, -v117
	v_fmac_f32_e32 v117, 0x3377d1cf, v109
	v_fmac_f32_e32 v117, 0x3f317217, v109
	v_mov_b32_e32 v109, v117
	v_min_f32_e32 v109, 0, v113
	v_mul_f32_e64 v113, |v113|, s84
	v_exp_f32_e32 v113, v113
	v_pk_add_f32 v[104:105], v[104:105], v[116:117] neg_lo:[0,1] neg_hi:[0,1]
	v_add_f32_e32 v113, 1.0, v113
	v_pk_mul_f32 v[104:105], v[104:105], s[76:77] op_sel_hi:[1,0]
	v_log_f32_e32 v113, v113
	s_nop 0
	v_mul_f32_e32 v120, 0x3f317217, v113
	v_fma_f32 v120, v113, s86, -v120
	v_fmac_f32_e32 v120, 0x3377d1cf, v113
	v_fmac_f32_e32 v120, 0x3f317217, v113
	v_mov_b32_e32 v113, v120
	v_add_f32_e32 v120, v110, v114
	v_mul_f32_e64 v110, |v118|, s84
	v_exp_f32_e32 v110, v110
	v_mul_f32_e64 v118, |v120|, s84
	v_exp_f32_e32 v118, v118
	v_pk_add_f32 v[108:109], v[108:109], v[112:113] neg_lo:[0,1] neg_hi:[0,1]
	v_add_f32_e32 v110, 1.0, v110
	v_add_f32_e32 v118, 1.0, v118
	v_pk_mul_f32 v[108:109], v[108:109], s[76:77] op_sel_hi:[1,0]
	v_log_f32_e32 v110, v110
	s_nop 0
	v_mul_f32_e32 v114, 0x3f317217, v110
	v_fma_f32 v114, v110, s86, -v114
	v_fmac_f32_e32 v114, 0x3377d1cf, v110
	v_fmac_f32_e32 v114, 0x3f317217, v110
	v_mov_b32_e32 v110, v114
	v_min_f32_e32 v110, 0, v120
	v_log_f32_e32 v118, v118
	s_nop 0
	v_mul_f32_e32 v120, 0x3f317217, v118
	v_fma_f32 v120, v118, s86, -v120
	v_fmac_f32_e32 v120, 0x3377d1cf, v118
	v_fmac_f32_e32 v120, 0x3f317217, v118
	v_mov_b32_e32 v118, v120
	v_add_f32_e32 v120, v111, v115
	v_mul_f32_e64 v111, |v119|, s84
	v_exp_f32_e32 v111, v111
	s_nop 0
	v_add_f32_e32 v111, 1.0, v111
	v_log_f32_e32 v111, v111
	s_nop 0
	v_mul_f32_e32 v115, 0x3f317217, v111
	v_fma_f32 v115, v111, s86, -v115
	v_fmac_f32_e32 v115, 0x3377d1cf, v111
	v_fmac_f32_e32 v115, 0x3f317217, v111
	v_mov_b32_e32 v111, v115
	v_pk_add_f32 v[106:107], v[106:107], v[114:115] neg_lo:[0,1] neg_hi:[0,1]
	v_mul_f32_e64 v114, |v120|, s84
	v_exp_f32_e32 v114, v114
	v_min_f32_e32 v111, 0, v120
	v_pk_mul_f32 v[106:107], v[106:107], s[76:77] op_sel_hi:[1,0]
	v_add_f32_e32 v114, 1.0, v114
	v_log_f32_e32 v114, v114
	s_nop 0
	v_mul_f32_e32 v115, 0x3f317217, v114
	v_fma_f32 v115, v114, s86, -v115
	v_fmac_f32_e32 v115, 0x3377d1cf, v114
	v_fmac_f32_e32 v115, 0x3f317217, v114
	v_mov_b32_e32 v114, v115
	v_mov_b32_e32 v119, v114
	v_pk_add_f32 v[110:111], v[110:111], v[118:119] neg_lo:[0,1] neg_hi:[0,1]
	v_pk_mul_f32 v[110:111], v[110:111], s[76:77] op_sel_hi:[1,0]
.LBB0_241:
	s_nop 0
	v_or_b32_e32 v114, 16, v130
	v_mov_b64_e32 v[112:113], s[8:9]
	v_mad_i64_i32 v[112:113], s[0:1], v114, s88, v[112:113]
	v_lshl_add_u64 v[112:113], v[148:149], 1, v[112:113]
	s_and_b64 vcc, exec, s[6:7]
	v_cvt_pk_bf16_f32 v104, v104, v105
	v_cvt_pk_bf16_f32 v105, v106, v107
	v_cvt_pk_bf16_f32 v106, v108, v109
	v_cvt_pk_bf16_f32 v107, v110, v111
	flat_store_dwordx4 v[112:113], v[104:107]
	s_cbranch_vccnz .LBB0_243
	global_load_dwordx4 v[104:107], v[146:147], off offset:-1520
	global_load_dwordx4 v[108:111], v[146:147], off offset:-1536
	s_waitcnt vmcnt(0)
	v_add_f32_e32 v104, v100, v104
	v_add_f32_e32 v108, v96, v108
	v_mul_f32_e64 v100, |v108|, s84
	v_exp_f32_e32 v100, v100
	v_min_f32_e32 v96, 0, v108
	v_add_f32_e32 v109, v97, v109
	v_add_f32_e32 v105, v101, v105
	v_add_f32_e32 v100, 1.0, v100
	v_mul_f32_e64 v101, |v109|, s84
	v_exp_f32_e32 v101, v101
	v_log_f32_e32 v100, v100
	v_add_f32_e32 v101, 1.0, v101
	v_min_f32_e32 v97, 0, v109
	v_add_f32_e32 v110, v98, v110
	v_mul_f32_e32 v108, 0x3f317217, v100
	v_fma_f32 v108, v100, s86, -v108
	v_fmac_f32_e32 v108, 0x3377d1cf, v100
	v_fmac_f32_e32 v108, 0x3f317217, v100
	v_min_f32_e32 v98, 0, v110
	v_add_f32_e32 v111, v99, v111
	v_mov_b32_e32 v100, v108
	v_min_f32_e32 v100, 0, v104
	v_mul_f32_e64 v104, |v104|, s84
	v_exp_f32_e32 v104, v104
	v_min_f32_e32 v99, 0, v111
	v_add_f32_e32 v104, 1.0, v104
	v_log_f32_e32 v104, v104
	s_nop 0
	v_mul_f32_e32 v114, 0x3f317217, v104
	v_fma_f32 v114, v104, s86, -v114
	v_fmac_f32_e32 v114, 0x3377d1cf, v104
	v_fmac_f32_e32 v114, 0x3f317217, v104
	v_mov_b32_e32 v104, v114
	v_log_f32_e32 v101, v101
	s_nop 0
	v_mul_f32_e32 v109, 0x3f317217, v101
	v_fma_f32 v109, v101, s86, -v109
	v_fmac_f32_e32 v109, 0x3377d1cf, v101
	v_fmac_f32_e32 v109, 0x3f317217, v101
	v_mov_b32_e32 v101, v109
	v_min_f32_e32 v101, 0, v105
	v_mul_f32_e64 v105, |v105|, s84
	v_exp_f32_e32 v105, v105
	v_pk_add_f32 v[96:97], v[96:97], v[108:109] neg_lo:[0,1] neg_hi:[0,1]
	v_add_f32_e32 v105, 1.0, v105
	v_pk_mul_f32 v[96:97], v[96:97], s[76:77] op_sel_hi:[1,0]
	v_log_f32_e32 v105, v105
	s_nop 0
	v_mul_f32_e32 v114, 0x3f317217, v105
	v_fma_f32 v114, v105, s86, -v114
	v_fmac_f32_e32 v114, 0x3377d1cf, v105
	v_fmac_f32_e32 v114, 0x3f317217, v105
	v_mov_b32_e32 v105, v114
	v_add_f32_e32 v114, v102, v106
	v_mul_f32_e64 v102, |v110|, s84
	v_exp_f32_e32 v102, v102
	v_mul_f32_e64 v110, |v114|, s84
	v_exp_f32_e32 v110, v110
	v_pk_add_f32 v[100:101], v[100:101], v[104:105] neg_lo:[0,1] neg_hi:[0,1]
	v_add_f32_e32 v102, 1.0, v102
	v_add_f32_e32 v110, 1.0, v110
	v_pk_mul_f32 v[100:101], v[100:101], s[76:77] op_sel_hi:[1,0]
	v_log_f32_e32 v102, v102
	s_nop 0
	v_mul_f32_e32 v106, 0x3f317217, v102
	v_fma_f32 v106, v102, s86, -v106
	v_fmac_f32_e32 v106, 0x3377d1cf, v102
	v_fmac_f32_e32 v106, 0x3f317217, v102
	v_mov_b32_e32 v102, v106
	v_min_f32_e32 v102, 0, v114
	v_log_f32_e32 v110, v110
	s_nop 0
	v_mul_f32_e32 v114, 0x3f317217, v110
	v_fma_f32 v114, v110, s86, -v114
	v_fmac_f32_e32 v114, 0x3377d1cf, v110
	v_fmac_f32_e32 v114, 0x3f317217, v110
	v_mov_b32_e32 v110, v114
	v_add_f32_e32 v114, v103, v107
	v_mul_f32_e64 v103, |v111|, s84
	v_exp_f32_e32 v103, v103
	s_nop 0
	v_add_f32_e32 v103, 1.0, v103
	v_log_f32_e32 v103, v103
	s_nop 0
	v_mul_f32_e32 v107, 0x3f317217, v103
	v_fma_f32 v107, v103, s86, -v107
	v_fmac_f32_e32 v107, 0x3377d1cf, v103
	v_fmac_f32_e32 v107, 0x3f317217, v103
	v_mov_b32_e32 v103, v107
	v_pk_add_f32 v[98:99], v[98:99], v[106:107] neg_lo:[0,1] neg_hi:[0,1]
	v_mul_f32_e64 v106, |v114|, s84
	v_exp_f32_e32 v106, v106
	v_min_f32_e32 v103, 0, v114
	v_pk_mul_f32 v[98:99], v[98:99], s[76:77] op_sel_hi:[1,0]
	v_add_f32_e32 v106, 1.0, v106
	v_log_f32_e32 v106, v106
	s_nop 0
	v_mul_f32_e32 v107, 0x3f317217, v106
	v_fma_f32 v107, v106, s86, -v107
	v_fmac_f32_e32 v107, 0x3377d1cf, v106
	v_fmac_f32_e32 v107, 0x3f317217, v106
	v_mov_b32_e32 v106, v107
	v_mov_b32_e32 v111, v106
	v_pk_add_f32 v[102:103], v[102:103], v[110:111] neg_lo:[0,1] neg_hi:[0,1]
	v_pk_mul_f32 v[102:103], v[102:103], s[76:77] op_sel_hi:[1,0]
.LBB0_243:
	s_and_b64 vcc, exec, s[6:7]
	v_cvt_pk_bf16_f32 v96, v96, v97
	v_cvt_pk_bf16_f32 v97, v98, v99
	v_cvt_pk_bf16_f32 v98, v100, v101
	v_cvt_pk_bf16_f32 v99, v102, v103
	flat_store_dwordx4 v[112:113], v[96:99] offset:256
	s_cbranch_vccnz .LBB0_245
	global_load_dwordx4 v[96:99], v[146:147], off offset:-2032
	global_load_dwordx4 v[100:103], v[146:147], off offset:-2048
	s_waitcnt vmcnt(0)
	v_add_f32_e32 v96, v92, v96
	v_add_f32_e32 v100, v88, v100
	v_mul_f32_e64 v92, |v100|, s84
	v_exp_f32_e32 v92, v92
	v_min_f32_e32 v88, 0, v100
	v_add_f32_e32 v101, v89, v101
	v_add_f32_e32 v97, v93, v97
	v_add_f32_e32 v92, 1.0, v92
	v_mul_f32_e64 v93, |v101|, s84
	v_exp_f32_e32 v93, v93
	v_log_f32_e32 v92, v92
	v_add_f32_e32 v93, 1.0, v93
	v_min_f32_e32 v89, 0, v101
	v_add_f32_e32 v102, v90, v102
	v_mul_f32_e32 v100, 0x3f317217, v92
	v_fma_f32 v100, v92, s86, -v100
	v_fmac_f32_e32 v100, 0x3377d1cf, v92
	v_fmac_f32_e32 v100, 0x3f317217, v92
	v_min_f32_e32 v90, 0, v102
	v_add_f32_e32 v103, v91, v103
	v_mov_b32_e32 v92, v100
	v_min_f32_e32 v92, 0, v96
	v_mul_f32_e64 v96, |v96|, s84
	v_exp_f32_e32 v96, v96
	v_min_f32_e32 v91, 0, v103
	v_add_f32_e32 v96, 1.0, v96
	v_log_f32_e32 v96, v96
	s_nop 0
	v_mul_f32_e32 v104, 0x3f317217, v96
	v_fma_f32 v104, v96, s86, -v104
	v_fmac_f32_e32 v104, 0x3377d1cf, v96
	v_fmac_f32_e32 v104, 0x3f317217, v96
	v_mov_b32_e32 v96, v104
	v_log_f32_e32 v93, v93
	s_nop 0
	v_mul_f32_e32 v101, 0x3f317217, v93
	v_fma_f32 v101, v93, s86, -v101
	v_fmac_f32_e32 v101, 0x3377d1cf, v93
	v_fmac_f32_e32 v101, 0x3f317217, v93
	v_mov_b32_e32 v93, v101
	v_min_f32_e32 v93, 0, v97
	v_mul_f32_e64 v97, |v97|, s84
	v_exp_f32_e32 v97, v97
	v_pk_add_f32 v[88:89], v[88:89], v[100:101] neg_lo:[0,1] neg_hi:[0,1]
	v_add_f32_e32 v97, 1.0, v97
	v_pk_mul_f32 v[88:89], v[88:89], s[76:77] op_sel_hi:[1,0]
	v_log_f32_e32 v97, v97
	s_nop 0
	v_mul_f32_e32 v104, 0x3f317217, v97
	v_fma_f32 v104, v97, s86, -v104
	v_fmac_f32_e32 v104, 0x3377d1cf, v97
	v_fmac_f32_e32 v104, 0x3f317217, v97
	v_mov_b32_e32 v97, v104
	v_add_f32_e32 v104, v94, v98
	v_mul_f32_e64 v94, |v102|, s84
	v_exp_f32_e32 v94, v94
	v_mul_f32_e64 v102, |v104|, s84
	v_exp_f32_e32 v102, v102
	v_pk_add_f32 v[92:93], v[92:93], v[96:97] neg_lo:[0,1] neg_hi:[0,1]
	v_add_f32_e32 v94, 1.0, v94
	v_add_f32_e32 v102, 1.0, v102
	v_pk_mul_f32 v[92:93], v[92:93], s[76:77] op_sel_hi:[1,0]
	v_log_f32_e32 v94, v94
	s_nop 0
	v_mul_f32_e32 v98, 0x3f317217, v94
	v_fma_f32 v98, v94, s86, -v98
	v_fmac_f32_e32 v98, 0x3377d1cf, v94
	v_fmac_f32_e32 v98, 0x3f317217, v94
	v_mov_b32_e32 v94, v98
	v_min_f32_e32 v94, 0, v104
	v_log_f32_e32 v102, v102
	s_nop 0
	v_mul_f32_e32 v104, 0x3f317217, v102
	v_fma_f32 v104, v102, s86, -v104
	v_fmac_f32_e32 v104, 0x3377d1cf, v102
	v_fmac_f32_e32 v104, 0x3f317217, v102
	v_mov_b32_e32 v102, v104
	v_add_f32_e32 v104, v95, v99
	v_mul_f32_e64 v95, |v103|, s84
	v_exp_f32_e32 v95, v95
	s_nop 0
	v_add_f32_e32 v95, 1.0, v95
	v_log_f32_e32 v95, v95
	s_nop 0
	v_mul_f32_e32 v99, 0x3f317217, v95
	v_fma_f32 v99, v95, s86, -v99
	v_fmac_f32_e32 v99, 0x3377d1cf, v95
	v_fmac_f32_e32 v99, 0x3f317217, v95
	v_mov_b32_e32 v95, v99
	v_pk_add_f32 v[90:91], v[90:91], v[98:99] neg_lo:[0,1] neg_hi:[0,1]
	v_mul_f32_e64 v98, |v104|, s84
	v_exp_f32_e32 v98, v98
	v_min_f32_e32 v95, 0, v104
	v_pk_mul_f32 v[90:91], v[90:91], s[76:77] op_sel_hi:[1,0]
	v_add_f32_e32 v98, 1.0, v98
	v_log_f32_e32 v98, v98
	s_nop 0
	v_mul_f32_e32 v99, 0x3f317217, v98
	v_fma_f32 v99, v98, s86, -v99
	v_fmac_f32_e32 v99, 0x3377d1cf, v98
	v_fmac_f32_e32 v99, 0x3f317217, v98
	v_mov_b32_e32 v98, v99
	v_mov_b32_e32 v103, v98
	v_pk_add_f32 v[94:95], v[94:95], v[102:103] neg_lo:[0,1] neg_hi:[0,1]
	v_pk_mul_f32 v[94:95], v[94:95], s[76:77] op_sel_hi:[1,0]
.LBB0_245:
	s_nop 0
	v_or_b32_e32 v98, 32, v130
	v_mov_b64_e32 v[96:97], s[8:9]
	v_mad_i64_i32 v[96:97], s[0:1], v98, s88, v[96:97]
	v_lshl_add_u64 v[96:97], v[148:149], 1, v[96:97]
	s_and_b64 vcc, exec, s[6:7]
	v_cvt_pk_bf16_f32 v88, v88, v89
	v_cvt_pk_bf16_f32 v89, v90, v91
	v_cvt_pk_bf16_f32 v90, v92, v93
	v_cvt_pk_bf16_f32 v91, v94, v95
	flat_store_dwordx4 v[96:97], v[88:91]
	s_cbranch_vccnz .LBB0_247
	global_load_dwordx4 v[88:91], v[146:147], off offset:-1520
	global_load_dwordx4 v[92:95], v[146:147], off offset:-1536
	s_waitcnt vmcnt(0)
	v_add_f32_e32 v88, v84, v88
	v_add_f32_e32 v92, v80, v92
	v_mul_f32_e64 v84, |v92|, s84
	v_exp_f32_e32 v84, v84
	v_min_f32_e32 v80, 0, v92
	v_add_f32_e32 v93, v81, v93
	v_add_f32_e32 v89, v85, v89
	v_add_f32_e32 v84, 1.0, v84
	v_mul_f32_e64 v85, |v93|, s84
	v_exp_f32_e32 v85, v85
	v_log_f32_e32 v84, v84
	v_add_f32_e32 v85, 1.0, v85
	v_min_f32_e32 v81, 0, v93
	v_add_f32_e32 v94, v82, v94
	v_mul_f32_e32 v92, 0x3f317217, v84
	v_fma_f32 v92, v84, s86, -v92
	v_fmac_f32_e32 v92, 0x3377d1cf, v84
	v_fmac_f32_e32 v92, 0x3f317217, v84
	v_min_f32_e32 v82, 0, v94
	v_add_f32_e32 v95, v83, v95
	v_mov_b32_e32 v84, v92
	v_min_f32_e32 v84, 0, v88
	v_mul_f32_e64 v88, |v88|, s84
	v_exp_f32_e32 v88, v88
	v_min_f32_e32 v83, 0, v95
	v_add_f32_e32 v88, 1.0, v88
	v_log_f32_e32 v88, v88
	s_nop 0
	v_mul_f32_e32 v98, 0x3f317217, v88
	v_fma_f32 v98, v88, s86, -v98
	v_fmac_f32_e32 v98, 0x3377d1cf, v88
	v_fmac_f32_e32 v98, 0x3f317217, v88
	v_mov_b32_e32 v88, v98
	v_log_f32_e32 v85, v85
	s_nop 0
	v_mul_f32_e32 v93, 0x3f317217, v85
	v_fma_f32 v93, v85, s86, -v93
	v_fmac_f32_e32 v93, 0x3377d1cf, v85
	v_fmac_f32_e32 v93, 0x3f317217, v85
	v_mov_b32_e32 v85, v93
	v_min_f32_e32 v85, 0, v89
	v_mul_f32_e64 v89, |v89|, s84
	v_exp_f32_e32 v89, v89
	v_pk_add_f32 v[80:81], v[80:81], v[92:93] neg_lo:[0,1] neg_hi:[0,1]
	v_add_f32_e32 v89, 1.0, v89
	v_pk_mul_f32 v[80:81], v[80:81], s[76:77] op_sel_hi:[1,0]
	v_log_f32_e32 v89, v89
	s_nop 0
	v_mul_f32_e32 v98, 0x3f317217, v89
	v_fma_f32 v98, v89, s86, -v98
	v_fmac_f32_e32 v98, 0x3377d1cf, v89
	v_fmac_f32_e32 v98, 0x3f317217, v89
	v_mov_b32_e32 v89, v98
	v_add_f32_e32 v98, v86, v90
	v_mul_f32_e64 v86, |v94|, s84
	v_exp_f32_e32 v86, v86
	v_mul_f32_e64 v94, |v98|, s84
	v_exp_f32_e32 v94, v94
	v_pk_add_f32 v[84:85], v[84:85], v[88:89] neg_lo:[0,1] neg_hi:[0,1]
	v_add_f32_e32 v86, 1.0, v86
	v_add_f32_e32 v94, 1.0, v94
	v_pk_mul_f32 v[84:85], v[84:85], s[76:77] op_sel_hi:[1,0]
	v_log_f32_e32 v86, v86
	s_nop 0
	v_mul_f32_e32 v90, 0x3f317217, v86
	v_fma_f32 v90, v86, s86, -v90
	v_fmac_f32_e32 v90, 0x3377d1cf, v86
	v_fmac_f32_e32 v90, 0x3f317217, v86
	v_mov_b32_e32 v86, v90
	v_min_f32_e32 v86, 0, v98
	v_log_f32_e32 v94, v94
	s_nop 0
	v_mul_f32_e32 v98, 0x3f317217, v94
	v_fma_f32 v98, v94, s86, -v98
	v_fmac_f32_e32 v98, 0x3377d1cf, v94
	v_fmac_f32_e32 v98, 0x3f317217, v94
	v_mov_b32_e32 v94, v98
	v_add_f32_e32 v98, v87, v91
	v_mul_f32_e64 v87, |v95|, s84
	v_exp_f32_e32 v87, v87
	s_nop 0
	v_add_f32_e32 v87, 1.0, v87
	v_log_f32_e32 v87, v87
	s_nop 0
	v_mul_f32_e32 v91, 0x3f317217, v87
	v_fma_f32 v91, v87, s86, -v91
	v_fmac_f32_e32 v91, 0x3377d1cf, v87
	v_fmac_f32_e32 v91, 0x3f317217, v87
	v_mov_b32_e32 v87, v91
	v_pk_add_f32 v[82:83], v[82:83], v[90:91] neg_lo:[0,1] neg_hi:[0,1]
	v_mul_f32_e64 v90, |v98|, s84
	v_exp_f32_e32 v90, v90
	v_min_f32_e32 v87, 0, v98
	v_pk_mul_f32 v[82:83], v[82:83], s[76:77] op_sel_hi:[1,0]
	v_add_f32_e32 v90, 1.0, v90
	v_log_f32_e32 v90, v90
	s_nop 0
	v_mul_f32_e32 v91, 0x3f317217, v90
	v_fma_f32 v91, v90, s86, -v91
	v_fmac_f32_e32 v91, 0x3377d1cf, v90
	v_fmac_f32_e32 v91, 0x3f317217, v90
	v_mov_b32_e32 v90, v91
	v_mov_b32_e32 v95, v90
	v_pk_add_f32 v[86:87], v[86:87], v[94:95] neg_lo:[0,1] neg_hi:[0,1]
	v_pk_mul_f32 v[86:87], v[86:87], s[76:77] op_sel_hi:[1,0]
.LBB0_247:
	s_and_b64 vcc, exec, s[6:7]
	v_cvt_pk_bf16_f32 v80, v80, v81
	v_cvt_pk_bf16_f32 v81, v82, v83
	v_cvt_pk_bf16_f32 v82, v84, v85
	v_cvt_pk_bf16_f32 v83, v86, v87
	flat_store_dwordx4 v[96:97], v[80:83] offset:256
	s_cbranch_vccnz .LBB0_249
	global_load_dwordx4 v[80:83], v[146:147], off offset:-2032
	global_load_dwordx4 v[84:87], v[146:147], off offset:-2048
	s_waitcnt vmcnt(0)
	v_add_f32_e32 v80, v76, v80
	v_add_f32_e32 v84, v72, v84
	v_mul_f32_e64 v76, |v84|, s84
	v_exp_f32_e32 v76, v76
	v_min_f32_e32 v72, 0, v84
	v_add_f32_e32 v85, v73, v85
	v_add_f32_e32 v81, v77, v81
	v_add_f32_e32 v76, 1.0, v76
	v_mul_f32_e64 v77, |v85|, s84
	v_exp_f32_e32 v77, v77
	v_log_f32_e32 v76, v76
	v_add_f32_e32 v77, 1.0, v77
	v_min_f32_e32 v73, 0, v85
	v_add_f32_e32 v86, v74, v86
	v_mul_f32_e32 v84, 0x3f317217, v76
	v_fma_f32 v84, v76, s86, -v84
	v_fmac_f32_e32 v84, 0x3377d1cf, v76
	v_fmac_f32_e32 v84, 0x3f317217, v76
	v_min_f32_e32 v74, 0, v86
	v_add_f32_e32 v87, v75, v87
	v_mov_b32_e32 v76, v84
	v_min_f32_e32 v76, 0, v80
	v_mul_f32_e64 v80, |v80|, s84
	v_exp_f32_e32 v80, v80
	v_min_f32_e32 v75, 0, v87
	v_add_f32_e32 v80, 1.0, v80
	v_log_f32_e32 v80, v80
	s_nop 0
	v_mul_f32_e32 v88, 0x3f317217, v80
	v_fma_f32 v88, v80, s86, -v88
	v_fmac_f32_e32 v88, 0x3377d1cf, v80
	v_fmac_f32_e32 v88, 0x3f317217, v80
	v_mov_b32_e32 v80, v88
	v_log_f32_e32 v77, v77
	s_nop 0
	v_mul_f32_e32 v85, 0x3f317217, v77
	v_fma_f32 v85, v77, s86, -v85
	v_fmac_f32_e32 v85, 0x3377d1cf, v77
	v_fmac_f32_e32 v85, 0x3f317217, v77
	v_mov_b32_e32 v77, v85
	v_min_f32_e32 v77, 0, v81
	v_mul_f32_e64 v81, |v81|, s84
	v_exp_f32_e32 v81, v81
	v_pk_add_f32 v[72:73], v[72:73], v[84:85] neg_lo:[0,1] neg_hi:[0,1]
	v_add_f32_e32 v81, 1.0, v81
	v_pk_mul_f32 v[72:73], v[72:73], s[76:77] op_sel_hi:[1,0]
	v_log_f32_e32 v81, v81
	s_nop 0
	v_mul_f32_e32 v88, 0x3f317217, v81
	v_fma_f32 v88, v81, s86, -v88
	v_fmac_f32_e32 v88, 0x3377d1cf, v81
	v_fmac_f32_e32 v88, 0x3f317217, v81
	v_mov_b32_e32 v81, v88
	v_add_f32_e32 v88, v78, v82
	v_mul_f32_e64 v78, |v86|, s84
	v_exp_f32_e32 v78, v78
	v_mul_f32_e64 v86, |v88|, s84
	v_exp_f32_e32 v86, v86
	v_pk_add_f32 v[76:77], v[76:77], v[80:81] neg_lo:[0,1] neg_hi:[0,1]
	v_add_f32_e32 v78, 1.0, v78
	v_add_f32_e32 v86, 1.0, v86
	v_pk_mul_f32 v[76:77], v[76:77], s[76:77] op_sel_hi:[1,0]
	v_log_f32_e32 v78, v78
	s_nop 0
	v_mul_f32_e32 v82, 0x3f317217, v78
	v_fma_f32 v82, v78, s86, -v82
	v_fmac_f32_e32 v82, 0x3377d1cf, v78
	v_fmac_f32_e32 v82, 0x3f317217, v78
	v_mov_b32_e32 v78, v82
	v_min_f32_e32 v78, 0, v88
	v_log_f32_e32 v86, v86
	s_nop 0
	v_mul_f32_e32 v88, 0x3f317217, v86
	v_fma_f32 v88, v86, s86, -v88
	v_fmac_f32_e32 v88, 0x3377d1cf, v86
	v_fmac_f32_e32 v88, 0x3f317217, v86
	v_mov_b32_e32 v86, v88
	v_add_f32_e32 v88, v79, v83
	v_mul_f32_e64 v79, |v87|, s84
	v_exp_f32_e32 v79, v79
	s_nop 0
	v_add_f32_e32 v79, 1.0, v79
	v_log_f32_e32 v79, v79
	s_nop 0
	v_mul_f32_e32 v83, 0x3f317217, v79
	v_fma_f32 v83, v79, s86, -v83
	v_fmac_f32_e32 v83, 0x3377d1cf, v79
	v_fmac_f32_e32 v83, 0x3f317217, v79
	v_mov_b32_e32 v79, v83
	v_pk_add_f32 v[74:75], v[74:75], v[82:83] neg_lo:[0,1] neg_hi:[0,1]
	v_mul_f32_e64 v82, |v88|, s84
	v_exp_f32_e32 v82, v82
	v_min_f32_e32 v79, 0, v88
	v_pk_mul_f32 v[74:75], v[74:75], s[76:77] op_sel_hi:[1,0]
	v_add_f32_e32 v82, 1.0, v82
	v_log_f32_e32 v82, v82
	s_nop 0
	v_mul_f32_e32 v83, 0x3f317217, v82
	v_fma_f32 v83, v82, s86, -v83
	v_fmac_f32_e32 v83, 0x3377d1cf, v82
	v_fmac_f32_e32 v83, 0x3f317217, v82
	v_mov_b32_e32 v82, v83
	v_mov_b32_e32 v87, v82
	v_pk_add_f32 v[78:79], v[78:79], v[86:87] neg_lo:[0,1] neg_hi:[0,1]
	v_pk_mul_f32 v[78:79], v[78:79], s[76:77] op_sel_hi:[1,0]
.LBB0_249:
	s_nop 0
	v_or_b32_e32 v82, 48, v130
	v_mov_b64_e32 v[80:81], s[8:9]
	v_mad_i64_i32 v[80:81], s[0:1], v82, s88, v[80:81]
	v_lshl_add_u64 v[80:81], v[148:149], 1, v[80:81]
	s_and_b64 vcc, exec, s[6:7]
	v_cvt_pk_bf16_f32 v72, v72, v73
	v_cvt_pk_bf16_f32 v73, v74, v75
	v_cvt_pk_bf16_f32 v74, v76, v77
	v_cvt_pk_bf16_f32 v75, v78, v79
	flat_store_dwordx4 v[80:81], v[72:75]
	s_cbranch_vccnz .LBB0_251
	global_load_dwordx4 v[72:75], v[146:147], off offset:-1520
	global_load_dwordx4 v[76:79], v[146:147], off offset:-1536
	s_waitcnt vmcnt(0)
	v_add_f32_e32 v72, v68, v72
	v_add_f32_e32 v76, v64, v76
	v_mul_f32_e64 v68, |v76|, s84
	v_exp_f32_e32 v68, v68
	v_min_f32_e32 v64, 0, v76
	v_add_f32_e32 v77, v65, v77
	v_add_f32_e32 v73, v69, v73
	v_add_f32_e32 v68, 1.0, v68
	v_mul_f32_e64 v69, |v77|, s84
	v_exp_f32_e32 v69, v69
	v_log_f32_e32 v68, v68
	v_add_f32_e32 v69, 1.0, v69
	v_min_f32_e32 v65, 0, v77
	v_add_f32_e32 v78, v66, v78
	v_mul_f32_e32 v76, 0x3f317217, v68
	v_fma_f32 v76, v68, s86, -v76
	v_fmac_f32_e32 v76, 0x3377d1cf, v68
	v_fmac_f32_e32 v76, 0x3f317217, v68
	v_min_f32_e32 v66, 0, v78
	v_add_f32_e32 v79, v67, v79
	v_mov_b32_e32 v68, v76
	v_min_f32_e32 v68, 0, v72
	v_mul_f32_e64 v72, |v72|, s84
	v_exp_f32_e32 v72, v72
	v_min_f32_e32 v67, 0, v79
	v_add_f32_e32 v72, 1.0, v72
	v_log_f32_e32 v72, v72
	s_nop 0
	v_mul_f32_e32 v82, 0x3f317217, v72
	v_fma_f32 v82, v72, s86, -v82
	v_fmac_f32_e32 v82, 0x3377d1cf, v72
	v_fmac_f32_e32 v82, 0x3f317217, v72
	v_mov_b32_e32 v72, v82
	v_log_f32_e32 v69, v69
	s_nop 0
	v_mul_f32_e32 v77, 0x3f317217, v69
	v_fma_f32 v77, v69, s86, -v77
	v_fmac_f32_e32 v77, 0x3377d1cf, v69
	v_fmac_f32_e32 v77, 0x3f317217, v69
	v_mov_b32_e32 v69, v77
	v_min_f32_e32 v69, 0, v73
	v_mul_f32_e64 v73, |v73|, s84
	v_exp_f32_e32 v73, v73
	v_pk_add_f32 v[64:65], v[64:65], v[76:77] neg_lo:[0,1] neg_hi:[0,1]
	v_add_f32_e32 v73, 1.0, v73
	v_pk_mul_f32 v[64:65], v[64:65], s[76:77] op_sel_hi:[1,0]
	v_log_f32_e32 v73, v73
	s_nop 0
	v_mul_f32_e32 v82, 0x3f317217, v73
	v_fma_f32 v82, v73, s86, -v82
	v_fmac_f32_e32 v82, 0x3377d1cf, v73
	v_fmac_f32_e32 v82, 0x3f317217, v73
	v_mov_b32_e32 v73, v82
	v_add_f32_e32 v82, v70, v74
	v_mul_f32_e64 v70, |v78|, s84
	v_exp_f32_e32 v70, v70
	v_mul_f32_e64 v78, |v82|, s84
	v_exp_f32_e32 v78, v78
	v_pk_add_f32 v[68:69], v[68:69], v[72:73] neg_lo:[0,1] neg_hi:[0,1]
	v_add_f32_e32 v70, 1.0, v70
	v_add_f32_e32 v78, 1.0, v78
	v_pk_mul_f32 v[68:69], v[68:69], s[76:77] op_sel_hi:[1,0]
	v_log_f32_e32 v70, v70
	s_nop 0
	v_mul_f32_e32 v74, 0x3f317217, v70
	v_fma_f32 v74, v70, s86, -v74
	v_fmac_f32_e32 v74, 0x3377d1cf, v70
	v_fmac_f32_e32 v74, 0x3f317217, v70
	v_mov_b32_e32 v70, v74
	v_min_f32_e32 v70, 0, v82
	v_log_f32_e32 v78, v78
	s_nop 0
	v_mul_f32_e32 v82, 0x3f317217, v78
	v_fma_f32 v82, v78, s86, -v82
	v_fmac_f32_e32 v82, 0x3377d1cf, v78
	v_fmac_f32_e32 v82, 0x3f317217, v78
	v_mov_b32_e32 v78, v82
	v_add_f32_e32 v82, v71, v75
	v_mul_f32_e64 v71, |v79|, s84
	v_exp_f32_e32 v71, v71
	s_nop 0
	v_add_f32_e32 v71, 1.0, v71
	v_log_f32_e32 v71, v71
	s_nop 0
	v_mul_f32_e32 v75, 0x3f317217, v71
	v_fma_f32 v75, v71, s86, -v75
	v_fmac_f32_e32 v75, 0x3377d1cf, v71
	v_fmac_f32_e32 v75, 0x3f317217, v71
	v_mov_b32_e32 v71, v75
	v_pk_add_f32 v[66:67], v[66:67], v[74:75] neg_lo:[0,1] neg_hi:[0,1]
	v_mul_f32_e64 v74, |v82|, s84
	v_exp_f32_e32 v74, v74
	v_min_f32_e32 v71, 0, v82
	v_pk_mul_f32 v[66:67], v[66:67], s[76:77] op_sel_hi:[1,0]
	v_add_f32_e32 v74, 1.0, v74
	v_log_f32_e32 v74, v74
	s_nop 0
	v_mul_f32_e32 v75, 0x3f317217, v74
	v_fma_f32 v75, v74, s86, -v75
	v_fmac_f32_e32 v75, 0x3377d1cf, v74
	v_fmac_f32_e32 v75, 0x3f317217, v74
	v_mov_b32_e32 v74, v75
	v_mov_b32_e32 v79, v74
	v_pk_add_f32 v[70:71], v[70:71], v[78:79] neg_lo:[0,1] neg_hi:[0,1]
	v_pk_mul_f32 v[70:71], v[70:71], s[76:77] op_sel_hi:[1,0]
.LBB0_251:
	s_and_b64 vcc, exec, s[6:7]
	v_cvt_pk_bf16_f32 v64, v64, v65
	v_cvt_pk_bf16_f32 v65, v66, v67
	v_cvt_pk_bf16_f32 v66, v68, v69
	v_cvt_pk_bf16_f32 v67, v70, v71
	flat_store_dwordx4 v[80:81], v[64:67] offset:256
	s_cbranch_vccnz .LBB0_253
	global_load_dwordx4 v[64:67], v[146:147], off offset:-2032
	global_load_dwordx4 v[68:71], v[146:147], off offset:-2048
	s_waitcnt vmcnt(0)
	v_add_f32_e32 v64, v60, v64
	v_add_f32_e32 v68, v56, v68
	v_mul_f32_e64 v60, |v68|, s84
	v_exp_f32_e32 v60, v60
	v_min_f32_e32 v56, 0, v68
	v_add_f32_e32 v69, v57, v69
	v_add_f32_e32 v65, v61, v65
	v_add_f32_e32 v60, 1.0, v60
	v_mul_f32_e64 v61, |v69|, s84
	v_exp_f32_e32 v61, v61
	v_log_f32_e32 v60, v60
	v_add_f32_e32 v61, 1.0, v61
	v_min_f32_e32 v57, 0, v69
	v_add_f32_e32 v70, v58, v70
	v_mul_f32_e32 v68, 0x3f317217, v60
	v_fma_f32 v68, v60, s86, -v68
	v_fmac_f32_e32 v68, 0x3377d1cf, v60
	v_fmac_f32_e32 v68, 0x3f317217, v60
	v_min_f32_e32 v58, 0, v70
	v_add_f32_e32 v71, v59, v71
	v_mov_b32_e32 v60, v68
	v_min_f32_e32 v60, 0, v64
	v_mul_f32_e64 v64, |v64|, s84
	v_exp_f32_e32 v64, v64
	v_min_f32_e32 v59, 0, v71
	v_add_f32_e32 v64, 1.0, v64
	v_log_f32_e32 v64, v64
	s_nop 0
	v_mul_f32_e32 v72, 0x3f317217, v64
	v_fma_f32 v72, v64, s86, -v72
	v_fmac_f32_e32 v72, 0x3377d1cf, v64
	v_fmac_f32_e32 v72, 0x3f317217, v64
	v_mov_b32_e32 v64, v72
	v_log_f32_e32 v61, v61
	s_nop 0
	v_mul_f32_e32 v69, 0x3f317217, v61
	v_fma_f32 v69, v61, s86, -v69
	v_fmac_f32_e32 v69, 0x3377d1cf, v61
	v_fmac_f32_e32 v69, 0x3f317217, v61
	v_mov_b32_e32 v61, v69
	v_min_f32_e32 v61, 0, v65
	v_mul_f32_e64 v65, |v65|, s84
	v_exp_f32_e32 v65, v65
	v_pk_add_f32 v[56:57], v[56:57], v[68:69] neg_lo:[0,1] neg_hi:[0,1]
	v_add_f32_e32 v65, 1.0, v65
	v_pk_mul_f32 v[56:57], v[56:57], s[76:77] op_sel_hi:[1,0]
	v_log_f32_e32 v65, v65
	s_nop 0
	v_mul_f32_e32 v72, 0x3f317217, v65
	v_fma_f32 v72, v65, s86, -v72
	v_fmac_f32_e32 v72, 0x3377d1cf, v65
	v_fmac_f32_e32 v72, 0x3f317217, v65
	v_mov_b32_e32 v65, v72
	v_add_f32_e32 v72, v62, v66
	v_mul_f32_e64 v62, |v70|, s84
	v_exp_f32_e32 v62, v62
	v_mul_f32_e64 v70, |v72|, s84
	v_exp_f32_e32 v70, v70
	v_pk_add_f32 v[60:61], v[60:61], v[64:65] neg_lo:[0,1] neg_hi:[0,1]
	v_add_f32_e32 v62, 1.0, v62
	v_add_f32_e32 v70, 1.0, v70
	v_pk_mul_f32 v[60:61], v[60:61], s[76:77] op_sel_hi:[1,0]
	v_log_f32_e32 v62, v62
	s_nop 0
	v_mul_f32_e32 v66, 0x3f317217, v62
	v_fma_f32 v66, v62, s86, -v66
	v_fmac_f32_e32 v66, 0x3377d1cf, v62
	v_fmac_f32_e32 v66, 0x3f317217, v62
	v_mov_b32_e32 v62, v66
	v_min_f32_e32 v62, 0, v72
	v_log_f32_e32 v70, v70
	s_nop 0
	v_mul_f32_e32 v72, 0x3f317217, v70
	v_fma_f32 v72, v70, s86, -v72
	v_fmac_f32_e32 v72, 0x3377d1cf, v70
	v_fmac_f32_e32 v72, 0x3f317217, v70
	v_mov_b32_e32 v70, v72
	v_add_f32_e32 v72, v63, v67
	v_mul_f32_e64 v63, |v71|, s84
	v_exp_f32_e32 v63, v63
	s_nop 0
	v_add_f32_e32 v63, 1.0, v63
	v_log_f32_e32 v63, v63
	s_nop 0
	v_mul_f32_e32 v67, 0x3f317217, v63
	v_fma_f32 v67, v63, s86, -v67
	v_fmac_f32_e32 v67, 0x3377d1cf, v63
	v_fmac_f32_e32 v67, 0x3f317217, v63
	v_mov_b32_e32 v63, v67
	v_pk_add_f32 v[58:59], v[58:59], v[66:67] neg_lo:[0,1] neg_hi:[0,1]
	v_mul_f32_e64 v66, |v72|, s84
	v_exp_f32_e32 v66, v66
	v_min_f32_e32 v63, 0, v72
	v_pk_mul_f32 v[58:59], v[58:59], s[76:77] op_sel_hi:[1,0]
	v_add_f32_e32 v66, 1.0, v66
	v_log_f32_e32 v66, v66
	s_nop 0
	v_mul_f32_e32 v67, 0x3f317217, v66
	v_fma_f32 v67, v66, s86, -v67
	v_fmac_f32_e32 v67, 0x3377d1cf, v66
	v_fmac_f32_e32 v67, 0x3f317217, v66
	v_mov_b32_e32 v66, v67
	v_mov_b32_e32 v71, v66
	v_pk_add_f32 v[62:63], v[62:63], v[70:71] neg_lo:[0,1] neg_hi:[0,1]
	v_pk_mul_f32 v[62:63], v[62:63], s[76:77] op_sel_hi:[1,0]
.LBB0_253:
	s_nop 0
	v_add_u32_e32 v66, 0x80, v130
	v_mov_b64_e32 v[64:65], s[8:9]
	v_mad_i64_i32 v[64:65], s[0:1], v66, s88, v[64:65]
	v_lshl_add_u64 v[64:65], v[148:149], 1, v[64:65]
	s_and_b64 vcc, exec, s[6:7]
	v_cvt_pk_bf16_f32 v56, v56, v57
	v_cvt_pk_bf16_f32 v57, v58, v59
	v_cvt_pk_bf16_f32 v58, v60, v61
	v_cvt_pk_bf16_f32 v59, v62, v63
	flat_store_dwordx4 v[64:65], v[56:59]
	s_cbranch_vccnz .LBB0_255
	global_load_dwordx4 v[56:59], v[146:147], off offset:-1520
	global_load_dwordx4 v[60:63], v[146:147], off offset:-1536
	s_waitcnt vmcnt(0)
	v_add_f32_e32 v56, v52, v56
	v_add_f32_e32 v60, v48, v60
	v_mul_f32_e64 v52, |v60|, s84
	v_exp_f32_e32 v52, v52
	v_min_f32_e32 v48, 0, v60
	v_add_f32_e32 v61, v49, v61
	v_add_f32_e32 v57, v53, v57
	v_add_f32_e32 v52, 1.0, v52
	v_mul_f32_e64 v53, |v61|, s84
	v_exp_f32_e32 v53, v53
	v_log_f32_e32 v52, v52
	v_add_f32_e32 v53, 1.0, v53
	v_min_f32_e32 v49, 0, v61
	v_add_f32_e32 v62, v50, v62
	v_mul_f32_e32 v60, 0x3f317217, v52
	v_fma_f32 v60, v52, s86, -v60
	v_fmac_f32_e32 v60, 0x3377d1cf, v52
	v_fmac_f32_e32 v60, 0x3f317217, v52
	v_min_f32_e32 v50, 0, v62
	v_add_f32_e32 v63, v51, v63
	v_mov_b32_e32 v52, v60
	v_min_f32_e32 v52, 0, v56
	v_mul_f32_e64 v56, |v56|, s84
	v_exp_f32_e32 v56, v56
	v_min_f32_e32 v51, 0, v63
	v_add_f32_e32 v56, 1.0, v56
	v_log_f32_e32 v56, v56
	s_nop 0
	v_mul_f32_e32 v66, 0x3f317217, v56
	v_fma_f32 v66, v56, s86, -v66
	v_fmac_f32_e32 v66, 0x3377d1cf, v56
	v_fmac_f32_e32 v66, 0x3f317217, v56
	v_mov_b32_e32 v56, v66
	v_log_f32_e32 v53, v53
	s_nop 0
	v_mul_f32_e32 v61, 0x3f317217, v53
	v_fma_f32 v61, v53, s86, -v61
	v_fmac_f32_e32 v61, 0x3377d1cf, v53
	v_fmac_f32_e32 v61, 0x3f317217, v53
	v_mov_b32_e32 v53, v61
	v_min_f32_e32 v53, 0, v57
	v_mul_f32_e64 v57, |v57|, s84
	v_exp_f32_e32 v57, v57
	v_pk_add_f32 v[48:49], v[48:49], v[60:61] neg_lo:[0,1] neg_hi:[0,1]
	v_add_f32_e32 v57, 1.0, v57
	v_pk_mul_f32 v[48:49], v[48:49], s[76:77] op_sel_hi:[1,0]
	v_log_f32_e32 v57, v57
	s_nop 0
	v_mul_f32_e32 v66, 0x3f317217, v57
	v_fma_f32 v66, v57, s86, -v66
	v_fmac_f32_e32 v66, 0x3377d1cf, v57
	v_fmac_f32_e32 v66, 0x3f317217, v57
	v_mov_b32_e32 v57, v66
	v_add_f32_e32 v66, v54, v58
	v_mul_f32_e64 v54, |v62|, s84
	v_exp_f32_e32 v54, v54
	v_mul_f32_e64 v62, |v66|, s84
	v_exp_f32_e32 v62, v62
	v_pk_add_f32 v[52:53], v[52:53], v[56:57] neg_lo:[0,1] neg_hi:[0,1]
	v_add_f32_e32 v54, 1.0, v54
	v_add_f32_e32 v62, 1.0, v62
	v_pk_mul_f32 v[52:53], v[52:53], s[76:77] op_sel_hi:[1,0]
	v_log_f32_e32 v54, v54
	s_nop 0
	v_mul_f32_e32 v58, 0x3f317217, v54
	v_fma_f32 v58, v54, s86, -v58
	v_fmac_f32_e32 v58, 0x3377d1cf, v54
	v_fmac_f32_e32 v58, 0x3f317217, v54
	v_mov_b32_e32 v54, v58
	v_min_f32_e32 v54, 0, v66
	v_log_f32_e32 v62, v62
	s_nop 0
	v_mul_f32_e32 v66, 0x3f317217, v62
	v_fma_f32 v66, v62, s86, -v66
	v_fmac_f32_e32 v66, 0x3377d1cf, v62
	v_fmac_f32_e32 v66, 0x3f317217, v62
	v_mov_b32_e32 v62, v66
	v_add_f32_e32 v66, v55, v59
	v_mul_f32_e64 v55, |v63|, s84
	v_exp_f32_e32 v55, v55
	s_nop 0
	v_add_f32_e32 v55, 1.0, v55
	v_log_f32_e32 v55, v55
	s_nop 0
	v_mul_f32_e32 v59, 0x3f317217, v55
	v_fma_f32 v59, v55, s86, -v59
	v_fmac_f32_e32 v59, 0x3377d1cf, v55
	v_fmac_f32_e32 v59, 0x3f317217, v55
	v_mov_b32_e32 v55, v59
	v_pk_add_f32 v[50:51], v[50:51], v[58:59] neg_lo:[0,1] neg_hi:[0,1]
	v_mul_f32_e64 v58, |v66|, s84
	v_exp_f32_e32 v58, v58
	v_min_f32_e32 v55, 0, v66
	v_pk_mul_f32 v[50:51], v[50:51], s[76:77] op_sel_hi:[1,0]
	v_add_f32_e32 v58, 1.0, v58
	v_log_f32_e32 v58, v58
	s_nop 0
	v_mul_f32_e32 v59, 0x3f317217, v58
	v_fma_f32 v59, v58, s86, -v59
	v_fmac_f32_e32 v59, 0x3377d1cf, v58
	v_fmac_f32_e32 v59, 0x3f317217, v58
	v_mov_b32_e32 v58, v59
	v_mov_b32_e32 v63, v58
	v_pk_add_f32 v[54:55], v[54:55], v[62:63] neg_lo:[0,1] neg_hi:[0,1]
	v_pk_mul_f32 v[54:55], v[54:55], s[76:77] op_sel_hi:[1,0]
.LBB0_255:
	s_and_b64 vcc, exec, s[6:7]
	v_cvt_pk_bf16_f32 v48, v48, v49
	v_cvt_pk_bf16_f32 v49, v50, v51
	v_cvt_pk_bf16_f32 v50, v52, v53
	v_cvt_pk_bf16_f32 v51, v54, v55
	flat_store_dwordx4 v[64:65], v[48:51] offset:256
	s_cbranch_vccnz .LBB0_257
	global_load_dwordx4 v[48:51], v[146:147], off offset:-2032
	global_load_dwordx4 v[52:55], v[146:147], off offset:-2048
	s_waitcnt vmcnt(0)
	v_add_f32_e32 v48, v44, v48
	v_add_f32_e32 v52, v40, v52
	v_mul_f32_e64 v44, |v52|, s84
	v_exp_f32_e32 v44, v44
	v_min_f32_e32 v40, 0, v52
	v_add_f32_e32 v53, v41, v53
	v_add_f32_e32 v49, v45, v49
	v_add_f32_e32 v44, 1.0, v44
	v_mul_f32_e64 v45, |v53|, s84
	v_exp_f32_e32 v45, v45
	v_log_f32_e32 v44, v44
	v_add_f32_e32 v45, 1.0, v45
	v_min_f32_e32 v41, 0, v53
	v_add_f32_e32 v54, v42, v54
	v_mul_f32_e32 v52, 0x3f317217, v44
	v_fma_f32 v52, v44, s86, -v52
	v_fmac_f32_e32 v52, 0x3377d1cf, v44
	v_fmac_f32_e32 v52, 0x3f317217, v44
	v_min_f32_e32 v42, 0, v54
	v_add_f32_e32 v55, v43, v55
	v_mov_b32_e32 v44, v52
	v_min_f32_e32 v44, 0, v48
	v_mul_f32_e64 v48, |v48|, s84
	v_exp_f32_e32 v48, v48
	v_min_f32_e32 v43, 0, v55
	v_add_f32_e32 v48, 1.0, v48
	v_log_f32_e32 v48, v48
	s_nop 0
	v_mul_f32_e32 v56, 0x3f317217, v48
	v_fma_f32 v56, v48, s86, -v56
	v_fmac_f32_e32 v56, 0x3377d1cf, v48
	v_fmac_f32_e32 v56, 0x3f317217, v48
	v_mov_b32_e32 v48, v56
	v_log_f32_e32 v45, v45
	s_nop 0
	v_mul_f32_e32 v53, 0x3f317217, v45
	v_fma_f32 v53, v45, s86, -v53
	v_fmac_f32_e32 v53, 0x3377d1cf, v45
	v_fmac_f32_e32 v53, 0x3f317217, v45
	v_mov_b32_e32 v45, v53
	v_min_f32_e32 v45, 0, v49
	v_mul_f32_e64 v49, |v49|, s84
	v_exp_f32_e32 v49, v49
	v_pk_add_f32 v[40:41], v[40:41], v[52:53] neg_lo:[0,1] neg_hi:[0,1]
	v_add_f32_e32 v49, 1.0, v49
	v_pk_mul_f32 v[40:41], v[40:41], s[76:77] op_sel_hi:[1,0]
	v_log_f32_e32 v49, v49
	s_nop 0
	v_mul_f32_e32 v56, 0x3f317217, v49
	v_fma_f32 v56, v49, s86, -v56
	v_fmac_f32_e32 v56, 0x3377d1cf, v49
	v_fmac_f32_e32 v56, 0x3f317217, v49
	v_mov_b32_e32 v49, v56
	v_add_f32_e32 v56, v46, v50
	v_mul_f32_e64 v46, |v54|, s84
	v_exp_f32_e32 v46, v46
	v_mul_f32_e64 v54, |v56|, s84
	v_exp_f32_e32 v54, v54
	v_pk_add_f32 v[44:45], v[44:45], v[48:49] neg_lo:[0,1] neg_hi:[0,1]
	v_add_f32_e32 v46, 1.0, v46
	v_add_f32_e32 v54, 1.0, v54
	v_pk_mul_f32 v[44:45], v[44:45], s[76:77] op_sel_hi:[1,0]
	v_log_f32_e32 v46, v46
	s_nop 0
	v_mul_f32_e32 v50, 0x3f317217, v46
	v_fma_f32 v50, v46, s86, -v50
	v_fmac_f32_e32 v50, 0x3377d1cf, v46
	v_fmac_f32_e32 v50, 0x3f317217, v46
	v_mov_b32_e32 v46, v50
	v_min_f32_e32 v46, 0, v56
	v_log_f32_e32 v54, v54
	s_nop 0
	v_mul_f32_e32 v56, 0x3f317217, v54
	v_fma_f32 v56, v54, s86, -v56
	v_fmac_f32_e32 v56, 0x3377d1cf, v54
	v_fmac_f32_e32 v56, 0x3f317217, v54
	v_mov_b32_e32 v54, v56
	v_add_f32_e32 v56, v47, v51
	v_mul_f32_e64 v47, |v55|, s84
	v_exp_f32_e32 v47, v47
	s_nop 0
	v_add_f32_e32 v47, 1.0, v47
	v_log_f32_e32 v47, v47
	s_nop 0
	v_mul_f32_e32 v51, 0x3f317217, v47
	v_fma_f32 v51, v47, s86, -v51
	v_fmac_f32_e32 v51, 0x3377d1cf, v47
	v_fmac_f32_e32 v51, 0x3f317217, v47
	v_mov_b32_e32 v47, v51
	v_pk_add_f32 v[42:43], v[42:43], v[50:51] neg_lo:[0,1] neg_hi:[0,1]
	v_mul_f32_e64 v50, |v56|, s84
	v_exp_f32_e32 v50, v50
	v_min_f32_e32 v47, 0, v56
	v_pk_mul_f32 v[42:43], v[42:43], s[76:77] op_sel_hi:[1,0]
	v_add_f32_e32 v50, 1.0, v50
	v_log_f32_e32 v50, v50
	s_nop 0
	v_mul_f32_e32 v51, 0x3f317217, v50
	v_fma_f32 v51, v50, s86, -v51
	v_fmac_f32_e32 v51, 0x3377d1cf, v50
	v_fmac_f32_e32 v51, 0x3f317217, v50
	v_mov_b32_e32 v50, v51
	v_mov_b32_e32 v55, v50
	v_pk_add_f32 v[46:47], v[46:47], v[54:55] neg_lo:[0,1] neg_hi:[0,1]
	v_pk_mul_f32 v[46:47], v[46:47], s[76:77] op_sel_hi:[1,0]
.LBB0_257:
	s_nop 0
	v_add_u32_e32 v50, 0x90, v130
	v_mov_b64_e32 v[48:49], s[8:9]
	v_mad_i64_i32 v[48:49], s[0:1], v50, s88, v[48:49]
	v_lshl_add_u64 v[48:49], v[148:149], 1, v[48:49]
	s_and_b64 vcc, exec, s[6:7]
	v_cvt_pk_bf16_f32 v40, v40, v41
	v_cvt_pk_bf16_f32 v41, v42, v43
	v_cvt_pk_bf16_f32 v42, v44, v45
	v_cvt_pk_bf16_f32 v43, v46, v47
	flat_store_dwordx4 v[48:49], v[40:43]
	s_cbranch_vccnz .LBB0_259
	global_load_dwordx4 v[40:43], v[146:147], off offset:-1520
	global_load_dwordx4 v[44:47], v[146:147], off offset:-1536
	s_waitcnt vmcnt(0)
	v_add_f32_e32 v40, v36, v40
	v_add_f32_e32 v44, v32, v44
	v_mul_f32_e64 v36, |v44|, s84
	v_exp_f32_e32 v36, v36
	v_min_f32_e32 v32, 0, v44
	v_add_f32_e32 v45, v33, v45
	v_add_f32_e32 v41, v37, v41
	v_add_f32_e32 v36, 1.0, v36
	v_mul_f32_e64 v37, |v45|, s84
	v_exp_f32_e32 v37, v37
	v_log_f32_e32 v36, v36
	v_add_f32_e32 v37, 1.0, v37
	v_min_f32_e32 v33, 0, v45
	v_add_f32_e32 v46, v34, v46
	v_mul_f32_e32 v44, 0x3f317217, v36
	v_fma_f32 v44, v36, s86, -v44
	v_fmac_f32_e32 v44, 0x3377d1cf, v36
	v_fmac_f32_e32 v44, 0x3f317217, v36
	v_min_f32_e32 v34, 0, v46
	v_add_f32_e32 v47, v35, v47
	v_mov_b32_e32 v36, v44
	v_min_f32_e32 v36, 0, v40
	v_mul_f32_e64 v40, |v40|, s84
	v_exp_f32_e32 v40, v40
	v_min_f32_e32 v35, 0, v47
	v_add_f32_e32 v40, 1.0, v40
	v_log_f32_e32 v40, v40
	s_nop 0
	v_mul_f32_e32 v50, 0x3f317217, v40
	v_fma_f32 v50, v40, s86, -v50
	v_fmac_f32_e32 v50, 0x3377d1cf, v40
	v_fmac_f32_e32 v50, 0x3f317217, v40
	v_mov_b32_e32 v40, v50
	v_log_f32_e32 v37, v37
	s_nop 0
	v_mul_f32_e32 v45, 0x3f317217, v37
	v_fma_f32 v45, v37, s86, -v45
	v_fmac_f32_e32 v45, 0x3377d1cf, v37
	v_fmac_f32_e32 v45, 0x3f317217, v37
	v_mov_b32_e32 v37, v45
	v_min_f32_e32 v37, 0, v41
	v_mul_f32_e64 v41, |v41|, s84
	v_exp_f32_e32 v41, v41
	v_pk_add_f32 v[32:33], v[32:33], v[44:45] neg_lo:[0,1] neg_hi:[0,1]
	v_add_f32_e32 v41, 1.0, v41
	v_pk_mul_f32 v[32:33], v[32:33], s[76:77] op_sel_hi:[1,0]
	v_log_f32_e32 v41, v41
	s_nop 0
	v_mul_f32_e32 v50, 0x3f317217, v41
	v_fma_f32 v50, v41, s86, -v50
	v_fmac_f32_e32 v50, 0x3377d1cf, v41
	v_fmac_f32_e32 v50, 0x3f317217, v41
	v_mov_b32_e32 v41, v50
	v_add_f32_e32 v50, v38, v42
	v_mul_f32_e64 v38, |v46|, s84
	v_exp_f32_e32 v38, v38
	v_mul_f32_e64 v46, |v50|, s84
	v_exp_f32_e32 v46, v46
	v_pk_add_f32 v[36:37], v[36:37], v[40:41] neg_lo:[0,1] neg_hi:[0,1]
	v_add_f32_e32 v38, 1.0, v38
	v_add_f32_e32 v46, 1.0, v46
	v_pk_mul_f32 v[36:37], v[36:37], s[76:77] op_sel_hi:[1,0]
	v_log_f32_e32 v38, v38
	s_nop 0
	v_mul_f32_e32 v42, 0x3f317217, v38
	v_fma_f32 v42, v38, s86, -v42
	v_fmac_f32_e32 v42, 0x3377d1cf, v38
	v_fmac_f32_e32 v42, 0x3f317217, v38
	v_mov_b32_e32 v38, v42
	v_min_f32_e32 v38, 0, v50
	v_log_f32_e32 v46, v46
	s_nop 0
	v_mul_f32_e32 v50, 0x3f317217, v46
	v_fma_f32 v50, v46, s86, -v50
	v_fmac_f32_e32 v50, 0x3377d1cf, v46
	v_fmac_f32_e32 v50, 0x3f317217, v46
	v_mov_b32_e32 v46, v50
	v_add_f32_e32 v50, v39, v43
	v_mul_f32_e64 v39, |v47|, s84
	v_exp_f32_e32 v39, v39
	s_nop 0
	v_add_f32_e32 v39, 1.0, v39
	v_log_f32_e32 v39, v39
	s_nop 0
	v_mul_f32_e32 v43, 0x3f317217, v39
	v_fma_f32 v43, v39, s86, -v43
	v_fmac_f32_e32 v43, 0x3377d1cf, v39
	v_fmac_f32_e32 v43, 0x3f317217, v39
	v_mov_b32_e32 v39, v43
	v_pk_add_f32 v[34:35], v[34:35], v[42:43] neg_lo:[0,1] neg_hi:[0,1]
	v_mul_f32_e64 v42, |v50|, s84
	v_exp_f32_e32 v42, v42
	v_min_f32_e32 v39, 0, v50
	v_pk_mul_f32 v[34:35], v[34:35], s[76:77] op_sel_hi:[1,0]
	v_add_f32_e32 v42, 1.0, v42
	v_log_f32_e32 v42, v42
	s_nop 0
	v_mul_f32_e32 v43, 0x3f317217, v42
	v_fma_f32 v43, v42, s86, -v43
	v_fmac_f32_e32 v43, 0x3377d1cf, v42
	v_fmac_f32_e32 v43, 0x3f317217, v42
	v_mov_b32_e32 v42, v43
	v_mov_b32_e32 v47, v42
	v_pk_add_f32 v[38:39], v[38:39], v[46:47] neg_lo:[0,1] neg_hi:[0,1]
	v_pk_mul_f32 v[38:39], v[38:39], s[76:77] op_sel_hi:[1,0]
.LBB0_259:
	s_and_b64 vcc, exec, s[6:7]
	v_cvt_pk_bf16_f32 v32, v32, v33
	v_cvt_pk_bf16_f32 v33, v34, v35
	v_cvt_pk_bf16_f32 v34, v36, v37
	v_cvt_pk_bf16_f32 v35, v38, v39
	flat_store_dwordx4 v[48:49], v[32:35] offset:256
	s_cbranch_vccnz .LBB0_261
	global_load_dwordx4 v[32:35], v[146:147], off offset:-2032
	global_load_dwordx4 v[36:39], v[146:147], off offset:-2048
	s_waitcnt vmcnt(0)
	v_add_f32_e32 v32, v28, v32
	v_add_f32_e32 v36, v24, v36
	v_mul_f32_e64 v28, |v36|, s84
	v_exp_f32_e32 v28, v28
	v_min_f32_e32 v24, 0, v36
	v_add_f32_e32 v37, v25, v37
	v_add_f32_e32 v33, v29, v33
	v_add_f32_e32 v28, 1.0, v28
	v_mul_f32_e64 v29, |v37|, s84
	v_exp_f32_e32 v29, v29
	v_log_f32_e32 v28, v28
	v_add_f32_e32 v29, 1.0, v29
	v_min_f32_e32 v25, 0, v37
	v_add_f32_e32 v38, v26, v38
	v_mul_f32_e32 v36, 0x3f317217, v28
	v_fma_f32 v36, v28, s86, -v36
	v_fmac_f32_e32 v36, 0x3377d1cf, v28
	v_fmac_f32_e32 v36, 0x3f317217, v28
	v_min_f32_e32 v26, 0, v38
	v_add_f32_e32 v39, v27, v39
	v_mov_b32_e32 v28, v36
	v_min_f32_e32 v28, 0, v32
	v_mul_f32_e64 v32, |v32|, s84
	v_exp_f32_e32 v32, v32
	v_min_f32_e32 v27, 0, v39
	v_add_f32_e32 v32, 1.0, v32
	v_log_f32_e32 v32, v32
	s_nop 0
	v_mul_f32_e32 v40, 0x3f317217, v32
	v_fma_f32 v40, v32, s86, -v40
	v_fmac_f32_e32 v40, 0x3377d1cf, v32
	v_fmac_f32_e32 v40, 0x3f317217, v32
	v_mov_b32_e32 v32, v40
	v_log_f32_e32 v29, v29
	s_nop 0
	v_mul_f32_e32 v37, 0x3f317217, v29
	v_fma_f32 v37, v29, s86, -v37
	v_fmac_f32_e32 v37, 0x3377d1cf, v29
	v_fmac_f32_e32 v37, 0x3f317217, v29
	v_mov_b32_e32 v29, v37
	v_min_f32_e32 v29, 0, v33
	v_mul_f32_e64 v33, |v33|, s84
	v_exp_f32_e32 v33, v33
	v_pk_add_f32 v[24:25], v[24:25], v[36:37] neg_lo:[0,1] neg_hi:[0,1]
	v_add_f32_e32 v33, 1.0, v33
	v_pk_mul_f32 v[24:25], v[24:25], s[76:77] op_sel_hi:[1,0]
	v_log_f32_e32 v33, v33
	s_nop 0
	v_mul_f32_e32 v40, 0x3f317217, v33
	v_fma_f32 v40, v33, s86, -v40
	v_fmac_f32_e32 v40, 0x3377d1cf, v33
	v_fmac_f32_e32 v40, 0x3f317217, v33
	v_mov_b32_e32 v33, v40
	v_add_f32_e32 v40, v30, v34
	v_mul_f32_e64 v30, |v38|, s84
	v_exp_f32_e32 v30, v30
	v_mul_f32_e64 v38, |v40|, s84
	v_exp_f32_e32 v38, v38
	v_pk_add_f32 v[28:29], v[28:29], v[32:33] neg_lo:[0,1] neg_hi:[0,1]
	v_add_f32_e32 v30, 1.0, v30
	v_add_f32_e32 v38, 1.0, v38
	v_pk_mul_f32 v[28:29], v[28:29], s[76:77] op_sel_hi:[1,0]
	v_log_f32_e32 v30, v30
	s_nop 0
	v_mul_f32_e32 v34, 0x3f317217, v30
	v_fma_f32 v34, v30, s86, -v34
	v_fmac_f32_e32 v34, 0x3377d1cf, v30
	v_fmac_f32_e32 v34, 0x3f317217, v30
	v_mov_b32_e32 v30, v34
	v_min_f32_e32 v30, 0, v40
	v_log_f32_e32 v38, v38
	s_nop 0
	v_mul_f32_e32 v40, 0x3f317217, v38
	v_fma_f32 v40, v38, s86, -v40
	v_fmac_f32_e32 v40, 0x3377d1cf, v38
	v_fmac_f32_e32 v40, 0x3f317217, v38
	v_mov_b32_e32 v38, v40
	v_add_f32_e32 v40, v31, v35
	v_mul_f32_e64 v31, |v39|, s84
	v_exp_f32_e32 v31, v31
	s_nop 0
	v_add_f32_e32 v31, 1.0, v31
	v_log_f32_e32 v31, v31
	s_nop 0
	v_mul_f32_e32 v35, 0x3f317217, v31
	v_fma_f32 v35, v31, s86, -v35
	v_fmac_f32_e32 v35, 0x3377d1cf, v31
	v_fmac_f32_e32 v35, 0x3f317217, v31
	v_mov_b32_e32 v31, v35
	v_pk_add_f32 v[26:27], v[26:27], v[34:35] neg_lo:[0,1] neg_hi:[0,1]
	v_mul_f32_e64 v34, |v40|, s84
	v_exp_f32_e32 v34, v34
	v_min_f32_e32 v31, 0, v40
	v_pk_mul_f32 v[26:27], v[26:27], s[76:77] op_sel_hi:[1,0]
	v_add_f32_e32 v34, 1.0, v34
	v_log_f32_e32 v34, v34
	s_nop 0
	v_mul_f32_e32 v35, 0x3f317217, v34
	v_fma_f32 v35, v34, s86, -v35
	v_fmac_f32_e32 v35, 0x3377d1cf, v34
	v_fmac_f32_e32 v35, 0x3f317217, v34
	v_mov_b32_e32 v34, v35
	v_mov_b32_e32 v39, v34
	v_pk_add_f32 v[30:31], v[30:31], v[38:39] neg_lo:[0,1] neg_hi:[0,1]
	v_pk_mul_f32 v[30:31], v[30:31], s[76:77] op_sel_hi:[1,0]
.LBB0_261:
	s_nop 0
	v_add_u32_e32 v34, 0xa0, v130
	v_mov_b64_e32 v[32:33], s[8:9]
	v_mad_i64_i32 v[32:33], s[0:1], v34, s88, v[32:33]
	v_lshl_add_u64 v[32:33], v[148:149], 1, v[32:33]
	s_and_b64 vcc, exec, s[6:7]
	v_cvt_pk_bf16_f32 v24, v24, v25
	v_cvt_pk_bf16_f32 v25, v26, v27
	v_cvt_pk_bf16_f32 v26, v28, v29
	v_cvt_pk_bf16_f32 v27, v30, v31
	flat_store_dwordx4 v[32:33], v[24:27]
	s_cbranch_vccnz .LBB0_263
	global_load_dwordx4 v[24:27], v[146:147], off offset:-1520
	global_load_dwordx4 v[28:31], v[146:147], off offset:-1536
	s_waitcnt vmcnt(0)
	v_add_f32_e32 v24, v20, v24
	v_add_f32_e32 v28, v16, v28
	v_mul_f32_e64 v20, |v28|, s84
	v_exp_f32_e32 v20, v20
	v_min_f32_e32 v16, 0, v28
	v_add_f32_e32 v29, v17, v29
	v_add_f32_e32 v25, v21, v25
	v_add_f32_e32 v20, 1.0, v20
	v_mul_f32_e64 v21, |v29|, s84
	v_exp_f32_e32 v21, v21
	v_log_f32_e32 v20, v20
	v_add_f32_e32 v21, 1.0, v21
	v_min_f32_e32 v17, 0, v29
	v_add_f32_e32 v30, v18, v30
	v_mul_f32_e32 v28, 0x3f317217, v20
	v_fma_f32 v28, v20, s86, -v28
	v_fmac_f32_e32 v28, 0x3377d1cf, v20
	v_fmac_f32_e32 v28, 0x3f317217, v20
	v_min_f32_e32 v18, 0, v30
	v_add_f32_e32 v31, v19, v31
	v_mov_b32_e32 v20, v28
	v_min_f32_e32 v20, 0, v24
	v_mul_f32_e64 v24, |v24|, s84
	v_exp_f32_e32 v24, v24
	v_min_f32_e32 v19, 0, v31
	v_add_f32_e32 v24, 1.0, v24
	v_log_f32_e32 v24, v24
	s_nop 0
	v_mul_f32_e32 v34, 0x3f317217, v24
	v_fma_f32 v34, v24, s86, -v34
	v_fmac_f32_e32 v34, 0x3377d1cf, v24
	v_fmac_f32_e32 v34, 0x3f317217, v24
	v_mov_b32_e32 v24, v34
	v_log_f32_e32 v21, v21
	s_nop 0
	v_mul_f32_e32 v29, 0x3f317217, v21
	v_fma_f32 v29, v21, s86, -v29
	v_fmac_f32_e32 v29, 0x3377d1cf, v21
	v_fmac_f32_e32 v29, 0x3f317217, v21
	v_mov_b32_e32 v21, v29
	v_min_f32_e32 v21, 0, v25
	v_mul_f32_e64 v25, |v25|, s84
	v_exp_f32_e32 v25, v25
	v_pk_add_f32 v[16:17], v[16:17], v[28:29] neg_lo:[0,1] neg_hi:[0,1]
	v_add_f32_e32 v25, 1.0, v25
	v_pk_mul_f32 v[16:17], v[16:17], s[76:77] op_sel_hi:[1,0]
	v_log_f32_e32 v25, v25
	s_nop 0
	v_mul_f32_e32 v34, 0x3f317217, v25
	v_fma_f32 v34, v25, s86, -v34
	v_fmac_f32_e32 v34, 0x3377d1cf, v25
	v_fmac_f32_e32 v34, 0x3f317217, v25
	v_mov_b32_e32 v25, v34
	v_add_f32_e32 v34, v22, v26
	v_mul_f32_e64 v22, |v30|, s84
	v_exp_f32_e32 v22, v22
	v_mul_f32_e64 v30, |v34|, s84
	v_exp_f32_e32 v30, v30
	v_pk_add_f32 v[20:21], v[20:21], v[24:25] neg_lo:[0,1] neg_hi:[0,1]
	v_add_f32_e32 v22, 1.0, v22
	v_add_f32_e32 v30, 1.0, v30
	v_pk_mul_f32 v[20:21], v[20:21], s[76:77] op_sel_hi:[1,0]
	v_log_f32_e32 v22, v22
	s_nop 0
	v_mul_f32_e32 v26, 0x3f317217, v22
	v_fma_f32 v26, v22, s86, -v26
	v_fmac_f32_e32 v26, 0x3377d1cf, v22
	v_fmac_f32_e32 v26, 0x3f317217, v22
	v_mov_b32_e32 v22, v26
	v_min_f32_e32 v22, 0, v34
	v_log_f32_e32 v30, v30
	s_nop 0
	v_mul_f32_e32 v34, 0x3f317217, v30
	v_fma_f32 v34, v30, s86, -v34
	v_fmac_f32_e32 v34, 0x3377d1cf, v30
	v_fmac_f32_e32 v34, 0x3f317217, v30
	v_mov_b32_e32 v30, v34
	v_add_f32_e32 v34, v23, v27
	v_mul_f32_e64 v23, |v31|, s84
	v_exp_f32_e32 v23, v23
	s_nop 0
	v_add_f32_e32 v23, 1.0, v23
	v_log_f32_e32 v23, v23
	s_nop 0
	v_mul_f32_e32 v27, 0x3f317217, v23
	v_fma_f32 v27, v23, s86, -v27
	v_fmac_f32_e32 v27, 0x3377d1cf, v23
	v_fmac_f32_e32 v27, 0x3f317217, v23
	v_mov_b32_e32 v23, v27
	v_pk_add_f32 v[18:19], v[18:19], v[26:27] neg_lo:[0,1] neg_hi:[0,1]
	v_mul_f32_e64 v26, |v34|, s84
	v_exp_f32_e32 v26, v26
	v_min_f32_e32 v23, 0, v34
	v_pk_mul_f32 v[18:19], v[18:19], s[76:77] op_sel_hi:[1,0]
	v_add_f32_e32 v26, 1.0, v26
	v_log_f32_e32 v26, v26
	s_nop 0
	v_mul_f32_e32 v27, 0x3f317217, v26
	v_fma_f32 v27, v26, s86, -v27
	v_fmac_f32_e32 v27, 0x3377d1cf, v26
	v_fmac_f32_e32 v27, 0x3f317217, v26
	v_mov_b32_e32 v26, v27
	v_mov_b32_e32 v31, v26
	v_pk_add_f32 v[22:23], v[22:23], v[30:31] neg_lo:[0,1] neg_hi:[0,1]
	v_pk_mul_f32 v[22:23], v[22:23], s[76:77] op_sel_hi:[1,0]
.LBB0_263:
	s_and_b64 vcc, exec, s[6:7]
	v_cvt_pk_bf16_f32 v16, v16, v17
	v_cvt_pk_bf16_f32 v17, v18, v19
	v_cvt_pk_bf16_f32 v18, v20, v21
	v_cvt_pk_bf16_f32 v19, v22, v23
	flat_store_dwordx4 v[32:33], v[16:19] offset:256
	s_cbranch_vccnz .LBB0_265
	global_load_dwordx4 v[16:19], v[146:147], off offset:-2032
	global_load_dwordx4 v[20:23], v[146:147], off offset:-2048
	s_waitcnt vmcnt(0)
	v_add_f32_e32 v16, v12, v16
	v_add_f32_e32 v20, v8, v20
	v_mul_f32_e64 v12, |v20|, s84
	v_exp_f32_e32 v12, v12
	v_min_f32_e32 v8, 0, v20
	v_add_f32_e32 v21, v9, v21
	v_add_f32_e32 v17, v13, v17
	v_add_f32_e32 v12, 1.0, v12
	v_mul_f32_e64 v13, |v21|, s84
	v_exp_f32_e32 v13, v13
	v_log_f32_e32 v12, v12
	v_add_f32_e32 v13, 1.0, v13
	v_min_f32_e32 v9, 0, v21
	v_add_f32_e32 v22, v10, v22
	v_mul_f32_e32 v20, 0x3f317217, v12
	v_fma_f32 v20, v12, s86, -v20
	v_fmac_f32_e32 v20, 0x3377d1cf, v12
	v_fmac_f32_e32 v20, 0x3f317217, v12
	v_min_f32_e32 v10, 0, v22
	v_add_f32_e32 v23, v11, v23
	v_mov_b32_e32 v12, v20
	v_min_f32_e32 v12, 0, v16
	v_mul_f32_e64 v16, |v16|, s84
	v_exp_f32_e32 v16, v16
	v_min_f32_e32 v11, 0, v23
	v_add_f32_e32 v16, 1.0, v16
	v_log_f32_e32 v16, v16
	s_nop 0
	v_mul_f32_e32 v24, 0x3f317217, v16
	v_fma_f32 v24, v16, s86, -v24
	v_fmac_f32_e32 v24, 0x3377d1cf, v16
	v_fmac_f32_e32 v24, 0x3f317217, v16
	v_mov_b32_e32 v16, v24
	v_log_f32_e32 v13, v13
	s_nop 0
	v_mul_f32_e32 v21, 0x3f317217, v13
	v_fma_f32 v21, v13, s86, -v21
	v_fmac_f32_e32 v21, 0x3377d1cf, v13
	v_fmac_f32_e32 v21, 0x3f317217, v13
	v_mov_b32_e32 v13, v21
	v_min_f32_e32 v13, 0, v17
	v_mul_f32_e64 v17, |v17|, s84
	v_exp_f32_e32 v17, v17
	v_pk_add_f32 v[8:9], v[8:9], v[20:21] neg_lo:[0,1] neg_hi:[0,1]
	v_add_f32_e32 v17, 1.0, v17
	v_pk_mul_f32 v[8:9], v[8:9], s[76:77] op_sel_hi:[1,0]
	v_log_f32_e32 v17, v17
	s_nop 0
	v_mul_f32_e32 v24, 0x3f317217, v17
	v_fma_f32 v24, v17, s86, -v24
	v_fmac_f32_e32 v24, 0x3377d1cf, v17
	v_fmac_f32_e32 v24, 0x3f317217, v17
	v_mov_b32_e32 v17, v24
	v_add_f32_e32 v24, v14, v18
	v_mul_f32_e64 v14, |v22|, s84
	v_exp_f32_e32 v14, v14
	v_mul_f32_e64 v22, |v24|, s84
	v_exp_f32_e32 v22, v22
	v_pk_add_f32 v[12:13], v[12:13], v[16:17] neg_lo:[0,1] neg_hi:[0,1]
	v_add_f32_e32 v14, 1.0, v14
	v_add_f32_e32 v22, 1.0, v22
	v_pk_mul_f32 v[12:13], v[12:13], s[76:77] op_sel_hi:[1,0]
	v_log_f32_e32 v14, v14
	s_nop 0
	v_mul_f32_e32 v18, 0x3f317217, v14
	v_fma_f32 v18, v14, s86, -v18
	v_fmac_f32_e32 v18, 0x3377d1cf, v14
	v_fmac_f32_e32 v18, 0x3f317217, v14
	v_mov_b32_e32 v14, v18
	v_min_f32_e32 v14, 0, v24
	v_log_f32_e32 v22, v22
	s_nop 0
	v_mul_f32_e32 v24, 0x3f317217, v22
	v_fma_f32 v24, v22, s86, -v24
	v_fmac_f32_e32 v24, 0x3377d1cf, v22
	v_fmac_f32_e32 v24, 0x3f317217, v22
	v_mov_b32_e32 v22, v24
	v_add_f32_e32 v24, v15, v19
	v_mul_f32_e64 v15, |v23|, s84
	v_exp_f32_e32 v15, v15
	s_nop 0
	v_add_f32_e32 v15, 1.0, v15
	v_log_f32_e32 v15, v15
	s_nop 0
	v_mul_f32_e32 v19, 0x3f317217, v15
	v_fma_f32 v19, v15, s86, -v19
	v_fmac_f32_e32 v19, 0x3377d1cf, v15
	v_fmac_f32_e32 v19, 0x3f317217, v15
	v_mov_b32_e32 v15, v19
	v_pk_add_f32 v[10:11], v[10:11], v[18:19] neg_lo:[0,1] neg_hi:[0,1]
	v_mul_f32_e64 v18, |v24|, s84
	v_exp_f32_e32 v18, v18
	v_min_f32_e32 v15, 0, v24
	v_pk_mul_f32 v[10:11], v[10:11], s[76:77] op_sel_hi:[1,0]
	v_add_f32_e32 v18, 1.0, v18
	v_log_f32_e32 v18, v18
	s_nop 0
	v_mul_f32_e32 v19, 0x3f317217, v18
	v_fma_f32 v19, v18, s86, -v19
	v_fmac_f32_e32 v19, 0x3377d1cf, v18
	v_fmac_f32_e32 v19, 0x3f317217, v18
	v_mov_b32_e32 v18, v19
	v_mov_b32_e32 v23, v18
	v_pk_add_f32 v[14:15], v[14:15], v[22:23] neg_lo:[0,1] neg_hi:[0,1]
	v_pk_mul_f32 v[14:15], v[14:15], s[76:77] op_sel_hi:[1,0]
.LBB0_265:
	s_nop 0
	v_add_u32_e32 v18, 0xb0, v130
	v_mov_b64_e32 v[16:17], s[8:9]
	v_mad_i64_i32 v[16:17], s[0:1], v18, s88, v[16:17]
	v_lshl_add_u64 v[16:17], v[148:149], 1, v[16:17]
	s_and_b64 vcc, exec, s[6:7]
	v_cvt_pk_bf16_f32 v8, v8, v9
	v_cvt_pk_bf16_f32 v9, v10, v11
	v_cvt_pk_bf16_f32 v10, v12, v13
	v_cvt_pk_bf16_f32 v11, v14, v15
	flat_store_dwordx4 v[16:17], v[8:11]
	s_cbranch_vccnz .LBB0_267
	global_load_dwordx4 v[8:11], v[146:147], off offset:-1520
	global_load_dwordx4 v[12:15], v[146:147], off offset:-1536
	s_waitcnt vmcnt(0)
	v_add_f32_e32 v8, v4, v8
	v_add_f32_e32 v12, v0, v12
	v_mul_f32_e64 v4, |v12|, s84
	v_exp_f32_e32 v4, v4
	v_min_f32_e32 v0, 0, v12
	v_add_f32_e32 v13, v1, v13
	v_add_f32_e32 v9, v5, v9
	v_add_f32_e32 v4, 1.0, v4
	v_mul_f32_e64 v5, |v13|, s84
	v_exp_f32_e32 v5, v5
	v_log_f32_e32 v4, v4
	v_add_f32_e32 v5, 1.0, v5
	v_min_f32_e32 v1, 0, v13
	v_add_f32_e32 v14, v2, v14
	v_mul_f32_e32 v12, 0x3f317217, v4
	v_fma_f32 v12, v4, s86, -v12
	v_fmac_f32_e32 v12, 0x3377d1cf, v4
	v_fmac_f32_e32 v12, 0x3f317217, v4
	v_min_f32_e32 v2, 0, v14
	v_add_f32_e32 v15, v3, v15
	v_mov_b32_e32 v4, v12
	v_min_f32_e32 v4, 0, v8
	v_mul_f32_e64 v8, |v8|, s84
	v_exp_f32_e32 v8, v8
	v_min_f32_e32 v3, 0, v15
	v_add_f32_e32 v8, 1.0, v8
	v_log_f32_e32 v8, v8
	s_nop 0
	v_mul_f32_e32 v18, 0x3f317217, v8
	v_fma_f32 v18, v8, s86, -v18
	v_fmac_f32_e32 v18, 0x3377d1cf, v8
	v_fmac_f32_e32 v18, 0x3f317217, v8
	v_mov_b32_e32 v8, v18
	v_log_f32_e32 v5, v5
	s_nop 0
	v_mul_f32_e32 v13, 0x3f317217, v5
	v_fma_f32 v13, v5, s86, -v13
	v_fmac_f32_e32 v13, 0x3377d1cf, v5
	v_fmac_f32_e32 v13, 0x3f317217, v5
	v_mov_b32_e32 v5, v13
	v_min_f32_e32 v5, 0, v9
	v_mul_f32_e64 v9, |v9|, s84
	v_exp_f32_e32 v9, v9
	v_pk_add_f32 v[0:1], v[0:1], v[12:13] neg_lo:[0,1] neg_hi:[0,1]
	v_add_f32_e32 v9, 1.0, v9
	v_pk_mul_f32 v[0:1], v[0:1], s[76:77] op_sel_hi:[1,0]
	v_log_f32_e32 v9, v9
	s_nop 0
	v_mul_f32_e32 v18, 0x3f317217, v9
	v_fma_f32 v18, v9, s86, -v18
	v_fmac_f32_e32 v18, 0x3377d1cf, v9
	v_fmac_f32_e32 v18, 0x3f317217, v9
	v_mov_b32_e32 v9, v18
	v_add_f32_e32 v18, v6, v10
	v_mul_f32_e64 v6, |v14|, s84
	v_exp_f32_e32 v6, v6
	v_mul_f32_e64 v14, |v18|, s84
	v_exp_f32_e32 v14, v14
	v_pk_add_f32 v[4:5], v[4:5], v[8:9] neg_lo:[0,1] neg_hi:[0,1]
	v_add_f32_e32 v6, 1.0, v6
	v_add_f32_e32 v14, 1.0, v14
	v_pk_mul_f32 v[4:5], v[4:5], s[76:77] op_sel_hi:[1,0]
	v_log_f32_e32 v6, v6
	s_nop 0
	v_mul_f32_e32 v10, 0x3f317217, v6
	v_fma_f32 v10, v6, s86, -v10
	v_fmac_f32_e32 v10, 0x3377d1cf, v6
	v_fmac_f32_e32 v10, 0x3f317217, v6
	v_mov_b32_e32 v6, v10
	v_min_f32_e32 v6, 0, v18
	v_log_f32_e32 v14, v14
	s_nop 0
	v_mul_f32_e32 v18, 0x3f317217, v14
	v_fma_f32 v18, v14, s86, -v18
	v_fmac_f32_e32 v18, 0x3377d1cf, v14
	v_fmac_f32_e32 v18, 0x3f317217, v14
	v_mov_b32_e32 v14, v18
	v_add_f32_e32 v18, v7, v11
	v_mul_f32_e64 v7, |v15|, s84
	v_exp_f32_e32 v7, v7
	s_nop 0
	v_add_f32_e32 v7, 1.0, v7
	v_log_f32_e32 v7, v7
	s_nop 0
	v_mul_f32_e32 v11, 0x3f317217, v7
	v_fma_f32 v11, v7, s86, -v11
	v_fmac_f32_e32 v11, 0x3377d1cf, v7
	v_fmac_f32_e32 v11, 0x3f317217, v7
	v_mov_b32_e32 v7, v11
	v_pk_add_f32 v[2:3], v[2:3], v[10:11] neg_lo:[0,1] neg_hi:[0,1]
	v_mul_f32_e64 v10, |v18|, s84
	v_exp_f32_e32 v10, v10
	v_min_f32_e32 v7, 0, v18
	v_pk_mul_f32 v[2:3], v[2:3], s[76:77] op_sel_hi:[1,0]
	v_add_f32_e32 v10, 1.0, v10
	v_log_f32_e32 v10, v10
	s_nop 0
	v_mul_f32_e32 v11, 0x3f317217, v10
	v_fma_f32 v11, v10, s86, -v11
	v_fmac_f32_e32 v11, 0x3377d1cf, v10
	v_fmac_f32_e32 v11, 0x3f317217, v10
	v_mov_b32_e32 v10, v11
	v_mov_b32_e32 v15, v10
	v_pk_add_f32 v[6:7], v[6:7], v[14:15] neg_lo:[0,1] neg_hi:[0,1]
	v_pk_mul_f32 v[6:7], v[6:7], s[76:77] op_sel_hi:[1,0]

.LBB0_286:
	s_lshl_b32 s20, s36, 6
	s_add_i32 s0, s20, 0x500
	s_mov_b32 s1, s83
	s_lshl_b64 s[0:1], s[0:1], 2
	s_add_u32 s0, s34, s0
	s_addc_u32 s1, s35, s1
	v_mov_b64_e32 v[4:5], s[0:1]
	flat_atomic_add v3, v[4:5], v209 sc0
	v_cvt_f32_u32_e32 v1, v2
	v_sub_u32_e32 v4, 0, v2
	v_rcp_iflag_f32_e32 v1, v1
	s_nop 0
	v_mul_f32_e32 v1, 0x4f7ffffe, v1
	v_cvt_u32_f32_e32 v1, v1
	v_mul_lo_u32 v4, v4, v1
	v_mul_hi_u32 v4, v1, v4
	v_add_u32_e32 v1, v1, v4
	s_waitcnt vmcnt(0) lgkmcnt(0)
	v_mul_hi_u32 v1, v3, v1
	v_mul_lo_u32 v4, v1, v2
	v_sub_u32_e32 v4, v3, v4
	v_cmp_ge_u32_e32 vcc, v4, v2
	v_add_u32_e32 v5, 1, v1
	s_nop 0
	v_cndmask_b32_e32 v1, v1, v5, vcc
	v_sub_u32_e32 v5, v4, v2
	v_cndmask_b32_e32 v4, v4, v5, vcc
	v_cmp_ge_u32_e32 vcc, v4, v2
	v_add_u32_e32 v4, 1, v1
	s_nop 0
	v_cndmask_b32_e32 v1, v1, v4, vcc
	v_add_u32_e32 v4, 1, v3
	v_mad_u64_u32 v[2:3], s[0:1], v2, v1, v[2:3]
	v_cmp_ne_u32_e32 vcc, v4, v2
	s_and_saveexec_b64 s[0:1], vcc
	s_xor_b64 s[0:1], exec, s[0:1]
	s_cbranch_execz .LBB0_299
	s_movk_i32 s2, 0xd40
	s_mov_b32 s3, s83
	s_lshl_b64 s[2:3], s[2:3], 2
	s_add_u32 s4, s34, s2
	s_addc_u32 s5, s35, s3
	v_mov_b64_e32 v[2:3], s[4:5]
	flat_load_dword v0, v[2:3] sc1
	s_waitcnt vmcnt(0) lgkmcnt(0)
	v_cmp_eq_u32_e32 vcc, v0, v1
	s_and_saveexec_b64 s[2:3], vcc
	s_cbranch_execz .LBB0_298
	s_mov_b32 s21, 1
	s_mov_b64 s[6:7], 0
	s_branch .LBB0_290

.LBB0_355:
	s_lshl_b32 s22, s38, 6
	s_add_i32 s82, s22, 0x500
	s_lshl_b64 s[0:1], s[82:83], 2
	s_add_u32 s0, s36, s0
	s_addc_u32 s1, s37, s1
	v_mov_b64_e32 v[4:5], s[0:1]
	flat_atomic_add v3, v[4:5], v209 sc0
	v_cvt_f32_u32_e32 v1, v2
	v_sub_u32_e32 v4, 0, v2
	v_rcp_iflag_f32_e32 v1, v1
	s_nop 0
	v_mul_f32_e32 v1, 0x4f7ffffe, v1
	v_cvt_u32_f32_e32 v1, v1
	v_mul_lo_u32 v4, v4, v1
	v_mul_hi_u32 v4, v1, v4
	v_add_u32_e32 v1, v1, v4
	s_waitcnt vmcnt(0) lgkmcnt(0)
	v_mul_hi_u32 v1, v3, v1
	v_mul_lo_u32 v4, v1, v2
	v_sub_u32_e32 v4, v3, v4
	v_cmp_ge_u32_e32 vcc, v4, v2
	v_add_u32_e32 v5, 1, v1
	s_nop 0
	v_cndmask_b32_e32 v1, v1, v5, vcc
	v_sub_u32_e32 v5, v4, v2
	v_cndmask_b32_e32 v4, v4, v5, vcc
	v_cmp_ge_u32_e32 vcc, v4, v2
	v_add_u32_e32 v4, 1, v1
	s_nop 0
	v_cndmask_b32_e32 v1, v1, v4, vcc
	v_add_u32_e32 v4, 1, v3
	v_mad_u64_u32 v[2:3], s[0:1], v2, v1, v[2:3]
	v_cmp_ne_u32_e32 vcc, v4, v2
	s_and_saveexec_b64 s[0:1], vcc
	s_xor_b64 s[0:1], exec, s[0:1]
	s_cbranch_execz .LBB0_368
	s_movk_i32 s82, 0xd40
	s_lshl_b64 s[2:3], s[82:83], 2
	s_add_u32 s6, s36, s2
	s_addc_u32 s7, s37, s3
	v_mov_b64_e32 v[2:3], s[6:7]
	flat_load_dword v0, v[2:3] sc1
	s_waitcnt vmcnt(0) lgkmcnt(0)
	v_cmp_eq_u32_e32 vcc, v0, v1
	s_and_saveexec_b64 s[2:3], vcc
	s_cbranch_execz .LBB0_367
	s_mov_b32 s23, 1
	s_mov_b64 s[8:9], 0
	s_branch .LBB0_359

.LBB0_440:
	s_lshl_b32 s20, s36, 6
	s_add_i32 s82, s20, 0x500
	s_lshl_b64 s[0:1], s[82:83], 2
	s_add_u32 s0, s34, s0
	s_addc_u32 s1, s35, s1
	v_mov_b64_e32 v[4:5], s[0:1]
	flat_atomic_add v3, v[4:5], v209 sc0
	v_cvt_f32_u32_e32 v1, v2
	v_sub_u32_e32 v4, 0, v2
	v_rcp_iflag_f32_e32 v1, v1
	s_nop 0
	v_mul_f32_e32 v1, 0x4f7ffffe, v1
	v_cvt_u32_f32_e32 v1, v1
	v_mul_lo_u32 v4, v4, v1
	v_mul_hi_u32 v4, v1, v4
	v_add_u32_e32 v1, v1, v4
	s_waitcnt vmcnt(0) lgkmcnt(0)
	v_mul_hi_u32 v1, v3, v1
	v_mul_lo_u32 v4, v1, v2
	v_sub_u32_e32 v4, v3, v4
	v_cmp_ge_u32_e32 vcc, v4, v2
	v_add_u32_e32 v5, 1, v1
	s_nop 0
	v_cndmask_b32_e32 v1, v1, v5, vcc
	v_sub_u32_e32 v5, v4, v2
	v_cndmask_b32_e32 v4, v4, v5, vcc
	v_cmp_ge_u32_e32 vcc, v4, v2
	v_add_u32_e32 v4, 1, v1
	s_nop 0
	v_cndmask_b32_e32 v1, v1, v4, vcc
	v_add_u32_e32 v4, 1, v3
	v_mad_u64_u32 v[2:3], s[0:1], v2, v1, v[2:3]
	v_cmp_ne_u32_e32 vcc, v4, v2
	s_and_saveexec_b64 s[0:1], vcc
	s_xor_b64 s[0:1], exec, s[0:1]
	s_cbranch_execz .LBB0_453
	s_movk_i32 s82, 0xd40
	s_lshl_b64 s[2:3], s[82:83], 2
	s_add_u32 s4, s34, s2
	s_addc_u32 s5, s35, s3
	v_mov_b64_e32 v[2:3], s[4:5]
	flat_load_dword v0, v[2:3] sc1
	s_waitcnt vmcnt(0) lgkmcnt(0)
	v_cmp_eq_u32_e32 vcc, v0, v1
	s_and_saveexec_b64 s[2:3], vcc
	s_cbranch_execz .LBB0_452
	s_mov_b32 s21, 1
	s_mov_b64 s[6:7], 0
	s_branch .LBB0_444
